# EpiAct/EpiScale epilogues: per-row rstd computed once per workgroup (2 contiguous loads per wave, quad reduction, 1 KB LDS exchange) instead of 8 scattered loads and a redundant reduction per wave
# speedup vs baseline: 1.0308x; 1.0097x over previous
; #define PG8_GAS __attribute__((address_space(1)))
; __device__ __forceinline__ unsigned pk2_(float lo, float hi) { f32x2c_t v = {lo, hi}; bf16x2c_t b = __builtin_convertvector(v, bf16x2c_t); return __builtin_bit_cast(unsigned, b); }
; __device__ __forceinline__ float row_rstd(const float* parts, int r, int fq) {
;     const f32x4 p = *(const PG8_GAS f32x4*)(parts + (size_t)r * 16 + 4 * fq);
;     float s = (p[0] + p[1]) + (p[2] + p[3]);
;     s += __shfl_xor(s, 16); s += __shfl_xor(s, 32);
;     return rsqrtf(s * (1.0f / 1024.0f) + RMS_EPS);
; }
; __device__ __forceinline__ float silu_f(float x) { return x * __builtin_amdgcn_rcpf(1.0f + __builtin_amdgcn_exp2f(-1.4426950408889634f * x)); }
;     __device__ __forceinline__ void operator()(const f32x4 (&acc)[2][2][4][2], const Unit& u, int wr, int wc, int fr, int fq) const {
;         const int row0 = u.pm * BM + wr * 64 + fr, col0 = u.pn * 128 + wc * 32 + 8 * fq;
;         float rs8[2][4];
; #pragma unroll
;         for (int ai = 0; ai < 2; ++ai)
; #pragma unroll
;             for (int m = 0; m < 4; ++m) rs8[ai][m] = row_rstd(parts, row0 + ai * HALF + m * 16, fq);
; #pragma unroll
;         for (int ai = 0; ai < 2; ++ai)
; #pragma unroll
;             for (int m = 0; m < 4; ++m) {
;                 const int r = row0 + ai * HALF + m * 16; const float s = rs8[ai][m];
;                 float o[8];
; #pragma unroll
;                 for (int n = 0; n < 2; ++n)
; #pragma unroll
;                     for (int i = 0; i < 4; ++i) o[4 * n + i] = silu_f(acc[ai][0][m][n][i] * s) * (acc[ai][1][m][n][i] * s);
;                 u32x4 w; w.x = pk2_(o[0], o[1]); w.y = pk2_(o[2], o[3]); w.z = pk2_(o[4], o[5]); w.w = pk2_(o[6], o[7]);
;                 *(PG8_GAS u32x4*)(O + (size_t)r * 2816 + col0) = w;
.LBB0_697:
	s_lshl_b32 s6, s6, 8
	v_mov_b32_e32 v132, v252
	s_add_i32 s6, s6, s53
	s_sub_i32 s99, s6, s53
	s_mov_b32 s98, s53
	s_lshl_b32 s100, s99, 6
	s_add_u32 s100, s80, s100
	s_addc_u32 s101, s81, 0
	v_lshrrev_b32_e32 v143, 6, v252
	v_and_b32_e32 v141, 63, v252
	v_lshlrev_b32_e32 v141, 4, v141
	v_lshl_or_b32 v141, v143, 11, v141
	global_load_dwordx4 v[168:171], v141, s[100:101]
	global_load_dwordx4 v[176:179], v141, s[100:101] offset:1024
	v_bfe_u32 v200, v132, 4, 2
	v_and_or_b32 v160, v132, 15, s6
	v_lshlrev_b32_e32 v132, 4, v200
	v_ashrrev_i32_e32 v161, 31, v160
	v_or_b32_e32 v156, 16, v160
	v_lshl_add_u64 v[190:191], s[80:81], 0, v[132:133]
	v_ashrrev_i32_e32 v157, 31, v156
	v_or_b32_e32 v152, 32, v160
	v_ashrrev_i32_e32 v153, 31, v152
	v_or_b32_e32 v148, 48, v160
	v_ashrrev_i32_e32 v149, 31, v148
	v_add_u32_e32 v146, 0x80, v160
	v_ashrrev_i32_e32 v147, 31, v146
	v_add_u32_e32 v144, 0x90, v160
	v_ashrrev_i32_e32 v145, 31, v144
	v_and_b32_e32 v140, 64, v165
	v_add_u32_e32 v147, 64, v140
	v_add_u32_e32 v142, 0xa0, v160
	v_add_u32_e32 v140, 0xb0, v160
	v_xor_b32_e32 v132, 16, v165
	v_cmp_lt_i32_e32 vcc, v132, v147
	v_xor_b32_e32 v145, 32, v165
	s_nop 0
	v_cndmask_b32_e32 v132, v165, v132, vcc
	v_lshlrev_b32_e32 v132, 2, v132
	v_cmp_lt_i32_e32 vcc, v145, v147
	v_mov_b64_e32 v[174:175], s[28:29]
	s_waitcnt vmcnt(0)
	v_add_f32_e32 v168, v168, v169
	v_add_f32_e32 v170, v170, v171
	v_add_f32_e32 v176, v176, v177
	v_add_f32_e32 v178, v178, v179
	v_add_f32_e32 v168, v168, v170
	v_add_f32_e32 v176, v176, v178
	v_mov_b32_e32 v170, 0x358637bd
	s_nop 0
	v_add_f32_dpp v169, v168, v168 quad_perm:[1,0,3,2] row_mask:0xf bank_mask:0xf
	v_add_f32_dpp v177, v176, v176 quad_perm:[1,0,3,2] row_mask:0xf bank_mask:0xf
	v_and_b32_e32 v171, 60, v252
	v_lshl_add_u32 v171, v143, 7, v171
	v_add_f32_dpp v168, v169, v169 quad_perm:[2,3,0,1] row_mask:0xf bank_mask:0xf
	v_add_f32_dpp v176, v177, v177 quad_perm:[2,3,0,1] row_mask:0xf bank_mask:0xf
	v_add_u32_e32 v171, 0x21000, v171
	v_and_b32_e32 v178, 15, v252
	v_fmamk_f32 v168, v168, 0x3a800000, v170
	v_fmamk_f32 v176, v176, 0x3a800000, v170
	v_add_u32_e32 v178, s98, v178
	v_rsq_f32_e32 v168, v168
	v_rsq_f32_e32 v176, v176
	v_lshlrev_b32_e32 v178, 2, v178
	v_add_u32_e32 v178, 0x21000, v178
	ds_write_b32 v171, v168
	ds_write_b32 v171, v176 offset:64
	s_waitcnt lgkmcnt(0)
	s_barrier
	ds_read_b32 v166, v178
	ds_read_b32 v172, v178 offset:64
	ds_read_b32 v164, v178 offset:128
	ds_read_b32 v162, v178 offset:192
	ds_read_b32 v158, v178 offset:512
	ds_read_b32 v154, v178 offset:576
	ds_read_b32 v150, v178 offset:640
	ds_read_b32 v132, v178 offset:704
	s_waitcnt lgkmcnt(0)
	s_lshl_b32 s6, s60, 7
	v_lshl_or_b32 v141, v200, 3, s6
	v_pk_mul_f32 v[124:125], v[124:125], v[166:167] op_sel_hi:[1,0]
	v_or_b32_e32 v168, s54, v141
	v_mul_f32_e32 v141, 0xbfb8aa3b, v124
	v_exp_f32_e32 v141, v141
	v_mul_f32_e32 v143, 0xbfb8aa3b, v125
	v_exp_f32_e32 v143, v143
	v_pk_mul_f32 v[126:127], v[126:127], v[166:167] op_sel_hi:[1,0]
	v_add_f32_e32 v141, 1.0, v141
	v_rcp_f32_e32 v170, v141
	v_add_f32_e32 v141, 1.0, v143
	v_mul_f32_e32 v143, 0xbfb8aa3b, v126
	v_exp_f32_e32 v143, v143
	v_mul_f32_e32 v145, 0xbfb8aa3b, v127
	v_exp_f32_e32 v145, v145
	v_rcp_f32_e32 v171, v141
	v_add_f32_e32 v141, 1.0, v143
	v_rcp_f32_e32 v174, v141
	v_add_f32_e32 v141, 1.0, v145
	v_rcp_f32_e32 v175, v141
	v_pk_mul_f32 v[124:125], v[124:125], v[170:171]
	v_pk_mul_f32 v[116:117], v[116:117], v[166:167] op_sel_hi:[1,0]
	v_pk_mul_f32 v[120:121], v[120:121], v[166:167] op_sel_hi:[1,0]
	v_pk_mul_f32 v[116:117], v[116:117], v[124:125]
	v_pk_mul_f32 v[124:125], v[126:127], v[174:175]
	v_mul_f32_e32 v126, 0xbfb8aa3b, v120
	v_mul_f32_e32 v127, 0xbfb8aa3b, v121
	v_exp_f32_e32 v126, v126
	v_exp_f32_e32 v127, v127
	v_pk_mul_f32 v[118:119], v[118:119], v[166:167] op_sel_hi:[1,0]
	v_pk_mul_f32 v[122:123], v[122:123], v[166:167] op_sel_hi:[1,0]
	v_pk_mul_f32 v[118:119], v[118:119], v[124:125]
	v_add_f32_e32 v124, 1.0, v126
	v_add_f32_e32 v125, 1.0, v127
	v_mul_f32_e32 v126, 0xbfb8aa3b, v122
	v_mul_f32_e32 v127, 0xbfb8aa3b, v123
	v_exp_f32_e32 v126, v126
	v_exp_f32_e32 v127, v127
	v_rcp_f32_e32 v124, v124
	v_rcp_f32_e32 v125, v125
	v_add_f32_e32 v126, 1.0, v126
	v_add_f32_e32 v127, 1.0, v127
	v_rcp_f32_e32 v126, v126
	v_rcp_f32_e32 v127, v127
	v_pk_mul_f32 v[120:121], v[120:121], v[124:125]
	v_pk_mul_f32 v[112:113], v[112:113], v[166:167] op_sel_hi:[1,0]
	v_pk_mul_f32 v[114:115], v[114:115], v[166:167] op_sel_hi:[1,0]
	v_pk_mul_f32 v[112:113], v[112:113], v[120:121]
	v_pk_mul_f32 v[120:121], v[122:123], v[126:127]
	v_ashrrev_i32_e32 v169, 31, v168
	v_pk_mul_f32 v[114:115], v[114:115], v[120:121]
	v_cvt_pk_bf16_f32 v116, v116, v117
	v_cvt_pk_bf16_f32 v117, v118, v119
	v_cvt_pk_bf16_f32 v118, v112, v113
	v_mov_b64_e32 v[112:113], s[14:15]
	v_cvt_pk_bf16_f32 v119, v114, v115
	v_mad_i64_i32 v[120:121], s[6:7], v160, s59, v[112:113]
	v_lshlrev_b64 v[114:115], 1, v[168:169]
	v_pk_mul_f32 v[108:109], v[108:109], v[172:173] op_sel_hi:[1,0]
	v_lshl_add_u64 v[120:121], v[120:121], 0, v[114:115]
	v_mul_f32_e32 v122, 0xbfb8aa3b, v108
	v_mul_f32_e32 v123, 0xbfb8aa3b, v109
	v_pk_mul_f32 v[110:111], v[110:111], v[172:173] op_sel_hi:[1,0]
	v_exp_f32_e32 v122, v122
	v_exp_f32_e32 v123, v123
	global_store_dwordx4 v[120:121], v[116:119], off
	v_pk_mul_f32 v[100:101], v[100:101], v[172:173] op_sel_hi:[1,0]
	v_pk_mul_f32 v[104:105], v[104:105], v[172:173] op_sel_hi:[1,0]
	v_mul_f32_e32 v118, 0xbfb8aa3b, v110
	v_mul_f32_e32 v119, 0xbfb8aa3b, v111
	v_exp_f32_e32 v118, v118
	v_exp_f32_e32 v119, v119
	v_add_f32_e32 v116, 1.0, v122
	v_add_f32_e32 v117, 1.0, v123
	v_rcp_f32_e32 v116, v116
	v_rcp_f32_e32 v117, v117
; #define PG8_GAS __attribute__((address_space(1)))
; __device__ __forceinline__ unsigned pk2_(float lo, float hi) { f32x2c_t v = {lo, hi}; bf16x2c_t b = __builtin_convertvector(v, bf16x2c_t); return __builtin_bit_cast(unsigned, b); }
; __device__ __forceinline__ float silu_f(float x) { return x * __builtin_amdgcn_rcpf(1.0f + __builtin_amdgcn_exp2f(-1.4426950408889634f * x)); }
;     __device__ __forceinline__ void operator()(const f32x4 (&acc)[2][2][4][2], const Unit& u, int wr, int wc, int fr, int fq) const {
;     ...
;             for (int m = 0; m < 4; ++m) {
;                 const int r = row0 + ai * HALF + m * 16; const float s = rs8[ai][m];
;                 float o[8];
; #pragma unroll
;                 for (int n = 0; n < 2; ++n)
; #pragma unroll
;                     for (int i = 0; i < 4; ++i) o[4 * n + i] = silu_f(acc[ai][0][m][n][i] * s) * (acc[ai][1][m][n][i] * s);
;                 u32x4 w; w.x = pk2_(o[0], o[1]); w.y = pk2_(o[2], o[3]); w.z = pk2_(o[4], o[5]); w.w = pk2_(o[6], o[7]);
;                 *(PG8_GAS u32x4*)(O + (size_t)r * 2816 + col0) = w;
	v_add_f32_e32 v118, 1.0, v118
	v_add_f32_e32 v119, 1.0, v119
	v_rcp_f32_e32 v118, v118
	v_rcp_f32_e32 v119, v119
	v_pk_mul_f32 v[108:109], v[108:109], v[116:117]
	v_pk_mul_f32 v[102:103], v[102:103], v[172:173] op_sel_hi:[1,0]
	v_pk_mul_f32 v[100:101], v[100:101], v[108:109]
	v_pk_mul_f32 v[108:109], v[110:111], v[118:119]
	v_mul_f32_e32 v110, 0xbfb8aa3b, v104
	v_mul_f32_e32 v111, 0xbfb8aa3b, v105
	v_exp_f32_e32 v110, v110
	v_exp_f32_e32 v111, v111
	v_pk_mul_f32 v[106:107], v[106:107], v[172:173] op_sel_hi:[1,0]
	v_pk_mul_f32 v[102:103], v[102:103], v[108:109]
	v_add_f32_e32 v108, 1.0, v110
	v_add_f32_e32 v109, 1.0, v111
	v_mul_f32_e32 v110, 0xbfb8aa3b, v106
	v_mul_f32_e32 v111, 0xbfb8aa3b, v107
	v_exp_f32_e32 v110, v110
	v_exp_f32_e32 v111, v111
	v_rcp_f32_e32 v108, v108
	v_rcp_f32_e32 v109, v109
	v_add_f32_e32 v110, 1.0, v110
	v_add_f32_e32 v111, 1.0, v111
	v_rcp_f32_e32 v110, v110
	v_rcp_f32_e32 v111, v111
	v_pk_mul_f32 v[104:105], v[104:105], v[108:109]
	v_pk_mul_f32 v[96:97], v[96:97], v[172:173] op_sel_hi:[1,0]
	v_pk_mul_f32 v[98:99], v[98:99], v[172:173] op_sel_hi:[1,0]
	v_pk_mul_f32 v[104:105], v[96:97], v[104:105]
	v_pk_mul_f32 v[96:97], v[106:107], v[110:111]
	v_pk_mul_f32 v[92:93], v[92:93], v[164:165] op_sel_hi:[1,0]
	v_pk_mul_f32 v[106:107], v[98:99], v[96:97]
	v_cvt_pk_bf16_f32 v96, v100, v101
	v_mad_i64_i32 v[100:101], s[6:7], v156, s59, v[112:113]
	v_cvt_pk_bf16_f32 v97, v102, v103
	v_cvt_pk_bf16_f32 v98, v104, v105
	v_cvt_pk_bf16_f32 v99, v106, v107
	v_lshl_add_u64 v[100:101], v[100:101], 0, v[114:115]
	v_mul_f32_e32 v102, 0xbfb8aa3b, v92
	v_mul_f32_e32 v103, 0xbfb8aa3b, v93
	v_pk_mul_f32 v[94:95], v[94:95], v[164:165] op_sel_hi:[1,0]
	v_exp_f32_e32 v102, v102
	v_exp_f32_e32 v103, v103
	global_store_dwordx4 v[100:101], v[96:99], off
	v_pk_mul_f32 v[84:85], v[84:85], v[164:165] op_sel_hi:[1,0]
	v_pk_mul_f32 v[88:89], v[88:89], v[164:165] op_sel_hi:[1,0]
	v_mul_f32_e32 v98, 0xbfb8aa3b, v94
	v_mul_f32_e32 v99, 0xbfb8aa3b, v95
	v_exp_f32_e32 v98, v98
	v_exp_f32_e32 v99, v99
	v_add_f32_e32 v96, 1.0, v102
	v_add_f32_e32 v97, 1.0, v103
	v_rcp_f32_e32 v96, v96
	v_rcp_f32_e32 v97, v97
	v_add_f32_e32 v98, 1.0, v98
	v_add_f32_e32 v99, 1.0, v99
	v_rcp_f32_e32 v98, v98
	v_rcp_f32_e32 v99, v99
	v_pk_mul_f32 v[92:93], v[92:93], v[96:97]
	v_pk_mul_f32 v[86:87], v[86:87], v[164:165] op_sel_hi:[1,0]
	v_pk_mul_f32 v[84:85], v[84:85], v[92:93]
	v_pk_mul_f32 v[92:93], v[94:95], v[98:99]
	v_mul_f32_e32 v94, 0xbfb8aa3b, v88
	v_mul_f32_e32 v95, 0xbfb8aa3b, v89
	v_exp_f32_e32 v94, v94
	v_exp_f32_e32 v95, v95
	v_pk_mul_f32 v[90:91], v[90:91], v[164:165] op_sel_hi:[1,0]
	v_pk_mul_f32 v[86:87], v[86:87], v[92:93]
	v_add_f32_e32 v92, 1.0, v94
	v_add_f32_e32 v93, 1.0, v95
	v_mul_f32_e32 v94, 0xbfb8aa3b, v90
	v_mul_f32_e32 v95, 0xbfb8aa3b, v91
	v_exp_f32_e32 v94, v94
	v_exp_f32_e32 v95, v95
	v_rcp_f32_e32 v92, v92
	v_rcp_f32_e32 v93, v93
	v_add_f32_e32 v94, 1.0, v94
	v_add_f32_e32 v95, 1.0, v95
	v_rcp_f32_e32 v94, v94
	v_rcp_f32_e32 v95, v95
	v_pk_mul_f32 v[88:89], v[88:89], v[92:93]
	v_pk_mul_f32 v[80:81], v[80:81], v[164:165] op_sel_hi:[1,0]
	v_pk_mul_f32 v[82:83], v[82:83], v[164:165] op_sel_hi:[1,0]
	v_pk_mul_f32 v[88:89], v[80:81], v[88:89]
	v_pk_mul_f32 v[80:81], v[90:91], v[94:95]
	v_pk_mul_f32 v[76:77], v[76:77], v[162:163] op_sel_hi:[1,0]
	v_pk_mul_f32 v[90:91], v[82:83], v[80:81]
	v_cvt_pk_bf16_f32 v80, v84, v85
	v_mad_i64_i32 v[84:85], s[6:7], v152, s59, v[112:113]
	v_cvt_pk_bf16_f32 v81, v86, v87
	v_cvt_pk_bf16_f32 v82, v88, v89
	v_cvt_pk_bf16_f32 v83, v90, v91
	v_lshl_add_u64 v[84:85], v[84:85], 0, v[114:115]
	v_mul_f32_e32 v86, 0xbfb8aa3b, v76
	v_mul_f32_e32 v87, 0xbfb8aa3b, v77
	v_pk_mul_f32 v[78:79], v[78:79], v[162:163] op_sel_hi:[1,0]
	v_exp_f32_e32 v86, v86
	v_exp_f32_e32 v87, v87
	global_store_dwordx4 v[84:85], v[80:83], off
	v_pk_mul_f32 v[68:69], v[68:69], v[162:163] op_sel_hi:[1,0]
	v_pk_mul_f32 v[72:73], v[72:73], v[162:163] op_sel_hi:[1,0]
	v_mul_f32_e32 v82, 0xbfb8aa3b, v78
	v_mul_f32_e32 v83, 0xbfb8aa3b, v79
	v_exp_f32_e32 v82, v82
	v_exp_f32_e32 v83, v83
	v_add_f32_e32 v80, 1.0, v86
	v_add_f32_e32 v81, 1.0, v87
	v_rcp_f32_e32 v80, v80
	v_rcp_f32_e32 v81, v81
	v_add_f32_e32 v82, 1.0, v82
	v_add_f32_e32 v83, 1.0, v83
	v_rcp_f32_e32 v82, v82
	v_rcp_f32_e32 v83, v83
	v_pk_mul_f32 v[76:77], v[76:77], v[80:81]
	v_pk_mul_f32 v[70:71], v[70:71], v[162:163] op_sel_hi:[1,0]
	v_pk_mul_f32 v[68:69], v[68:69], v[76:77]
	v_pk_mul_f32 v[76:77], v[78:79], v[82:83]
	v_mul_f32_e32 v78, 0xbfb8aa3b, v72
	v_mul_f32_e32 v79, 0xbfb8aa3b, v73
	v_exp_f32_e32 v78, v78
	v_exp_f32_e32 v79, v79
	v_pk_mul_f32 v[74:75], v[74:75], v[162:163] op_sel_hi:[1,0]
	v_pk_mul_f32 v[70:71], v[70:71], v[76:77]
	v_add_f32_e32 v76, 1.0, v78
	v_add_f32_e32 v77, 1.0, v79
	v_mul_f32_e32 v78, 0xbfb8aa3b, v74
	v_mul_f32_e32 v79, 0xbfb8aa3b, v75
	v_exp_f32_e32 v78, v78
	v_exp_f32_e32 v79, v79
	v_rcp_f32_e32 v76, v76
	v_rcp_f32_e32 v77, v77
	v_add_f32_e32 v78, 1.0, v78
	v_add_f32_e32 v79, 1.0, v79
	v_rcp_f32_e32 v78, v78
	v_rcp_f32_e32 v79, v79
	v_pk_mul_f32 v[72:73], v[72:73], v[76:77]
	v_pk_mul_f32 v[64:65], v[64:65], v[162:163] op_sel_hi:[1,0]
	v_pk_mul_f32 v[66:67], v[66:67], v[162:163] op_sel_hi:[1,0]
	v_pk_mul_f32 v[72:73], v[64:65], v[72:73]
	v_pk_mul_f32 v[64:65], v[74:75], v[78:79]
	v_pk_mul_f32 v[60:61], v[60:61], v[158:159] op_sel_hi:[1,0]
	v_pk_mul_f32 v[74:75], v[66:67], v[64:65]
	v_cvt_pk_bf16_f32 v64, v68, v69
	v_mad_i64_i32 v[68:69], s[6:7], v148, s59, v[112:113]
	v_cvt_pk_bf16_f32 v65, v70, v71
	v_cvt_pk_bf16_f32 v66, v72, v73
	v_cvt_pk_bf16_f32 v67, v74, v75
	v_lshl_add_u64 v[68:69], v[68:69], 0, v[114:115]
	v_mul_f32_e32 v70, 0xbfb8aa3b, v60
; #define PG8_GAS __attribute__((address_space(1)))
; __device__ __forceinline__ unsigned pk2_(float lo, float hi) { f32x2c_t v = {lo, hi}; bf16x2c_t b = __builtin_convertvector(v, bf16x2c_t); return __builtin_bit_cast(unsigned, b); }
; __device__ __forceinline__ float silu_f(float x) { return x * __builtin_amdgcn_rcpf(1.0f + __builtin_amdgcn_exp2f(-1.4426950408889634f * x)); }
;     __device__ __forceinline__ void operator()(const f32x4 (&acc)[2][2][4][2], const Unit& u, int wr, int wc, int fr, int fq) const {
;     ...
;             for (int m = 0; m < 4; ++m) {
;                 const int r = row0 + ai * HALF + m * 16; const float s = rs8[ai][m];
;                 float o[8];
; #pragma unroll
;                 for (int n = 0; n < 2; ++n)
; #pragma unroll
;                     for (int i = 0; i < 4; ++i) o[4 * n + i] = silu_f(acc[ai][0][m][n][i] * s) * (acc[ai][1][m][n][i] * s);
;                 u32x4 w; w.x = pk2_(o[0], o[1]); w.y = pk2_(o[2], o[3]); w.z = pk2_(o[4], o[5]); w.w = pk2_(o[6], o[7]);
;                 *(PG8_GAS u32x4*)(O + (size_t)r * 2816 + col0) = w;
	v_mul_f32_e32 v71, 0xbfb8aa3b, v61
	v_pk_mul_f32 v[62:63], v[62:63], v[158:159] op_sel_hi:[1,0]
	v_exp_f32_e32 v70, v70
	v_exp_f32_e32 v71, v71
	global_store_dwordx4 v[68:69], v[64:67], off
	v_pk_mul_f32 v[52:53], v[52:53], v[158:159] op_sel_hi:[1,0]
	v_pk_mul_f32 v[56:57], v[56:57], v[158:159] op_sel_hi:[1,0]
	v_mul_f32_e32 v66, 0xbfb8aa3b, v62
	v_mul_f32_e32 v67, 0xbfb8aa3b, v63
	v_exp_f32_e32 v66, v66
	v_exp_f32_e32 v67, v67
	v_add_f32_e32 v64, 1.0, v70
	v_add_f32_e32 v65, 1.0, v71
	v_rcp_f32_e32 v64, v64
	v_rcp_f32_e32 v65, v65
	v_add_f32_e32 v66, 1.0, v66
	v_add_f32_e32 v67, 1.0, v67
	v_rcp_f32_e32 v66, v66
	v_rcp_f32_e32 v67, v67
	v_pk_mul_f32 v[60:61], v[60:61], v[64:65]
	v_pk_mul_f32 v[54:55], v[54:55], v[158:159] op_sel_hi:[1,0]
	v_pk_mul_f32 v[52:53], v[52:53], v[60:61]
	v_pk_mul_f32 v[60:61], v[62:63], v[66:67]
	v_mul_f32_e32 v62, 0xbfb8aa3b, v56
	v_mul_f32_e32 v63, 0xbfb8aa3b, v57
	v_exp_f32_e32 v62, v62
	v_exp_f32_e32 v63, v63
	v_pk_mul_f32 v[58:59], v[58:59], v[158:159] op_sel_hi:[1,0]
	v_pk_mul_f32 v[54:55], v[54:55], v[60:61]
	v_add_f32_e32 v60, 1.0, v62
	v_add_f32_e32 v61, 1.0, v63
	v_mul_f32_e32 v62, 0xbfb8aa3b, v58
	v_mul_f32_e32 v63, 0xbfb8aa3b, v59
	v_exp_f32_e32 v62, v62
	v_exp_f32_e32 v63, v63
	v_rcp_f32_e32 v60, v60
	v_rcp_f32_e32 v61, v61
	v_add_f32_e32 v62, 1.0, v62
	v_add_f32_e32 v63, 1.0, v63
	v_rcp_f32_e32 v62, v62
	v_rcp_f32_e32 v63, v63
	v_pk_mul_f32 v[56:57], v[56:57], v[60:61]
	v_pk_mul_f32 v[48:49], v[48:49], v[158:159] op_sel_hi:[1,0]
	v_pk_mul_f32 v[50:51], v[50:51], v[158:159] op_sel_hi:[1,0]
	v_pk_mul_f32 v[56:57], v[48:49], v[56:57]
	v_pk_mul_f32 v[48:49], v[58:59], v[62:63]
	v_pk_mul_f32 v[44:45], v[44:45], v[154:155] op_sel_hi:[1,0]
	v_pk_mul_f32 v[58:59], v[50:51], v[48:49]
	v_cvt_pk_bf16_f32 v48, v52, v53
	v_mad_i64_i32 v[52:53], s[6:7], v146, s59, v[112:113]
	v_cvt_pk_bf16_f32 v49, v54, v55
	v_cvt_pk_bf16_f32 v50, v56, v57
	v_cvt_pk_bf16_f32 v51, v58, v59
	v_lshl_add_u64 v[52:53], v[52:53], 0, v[114:115]
	v_mul_f32_e32 v54, 0xbfb8aa3b, v44
	v_mul_f32_e32 v55, 0xbfb8aa3b, v45
	v_pk_mul_f32 v[46:47], v[46:47], v[154:155] op_sel_hi:[1,0]
	v_exp_f32_e32 v54, v54
	v_exp_f32_e32 v55, v55
	global_store_dwordx4 v[52:53], v[48:51], off
	v_pk_mul_f32 v[36:37], v[36:37], v[154:155] op_sel_hi:[1,0]
	v_pk_mul_f32 v[40:41], v[40:41], v[154:155] op_sel_hi:[1,0]
	v_mul_f32_e32 v50, 0xbfb8aa3b, v46
	v_mul_f32_e32 v51, 0xbfb8aa3b, v47
	v_exp_f32_e32 v50, v50
	v_exp_f32_e32 v51, v51
	v_add_f32_e32 v48, 1.0, v54
	v_add_f32_e32 v49, 1.0, v55
	v_rcp_f32_e32 v48, v48
	v_rcp_f32_e32 v49, v49
	v_add_f32_e32 v50, 1.0, v50
	v_add_f32_e32 v51, 1.0, v51
	v_rcp_f32_e32 v50, v50
	v_rcp_f32_e32 v51, v51
	v_pk_mul_f32 v[44:45], v[44:45], v[48:49]
	v_pk_mul_f32 v[38:39], v[38:39], v[154:155] op_sel_hi:[1,0]
	v_pk_mul_f32 v[36:37], v[36:37], v[44:45]
	v_pk_mul_f32 v[44:45], v[46:47], v[50:51]
	v_mul_f32_e32 v46, 0xbfb8aa3b, v40
	v_mul_f32_e32 v47, 0xbfb8aa3b, v41
	v_exp_f32_e32 v46, v46
	v_exp_f32_e32 v47, v47
	v_pk_mul_f32 v[42:43], v[42:43], v[154:155] op_sel_hi:[1,0]
	v_pk_mul_f32 v[38:39], v[38:39], v[44:45]
	v_add_f32_e32 v44, 1.0, v46
	v_add_f32_e32 v45, 1.0, v47
	v_mul_f32_e32 v46, 0xbfb8aa3b, v42
	v_mul_f32_e32 v47, 0xbfb8aa3b, v43
	v_exp_f32_e32 v46, v46
	v_exp_f32_e32 v47, v47
	v_rcp_f32_e32 v44, v44
	v_rcp_f32_e32 v45, v45
	v_add_f32_e32 v46, 1.0, v46
	v_add_f32_e32 v47, 1.0, v47
	v_rcp_f32_e32 v46, v46
	v_rcp_f32_e32 v47, v47
	v_pk_mul_f32 v[40:41], v[40:41], v[44:45]
	v_pk_mul_f32 v[32:33], v[32:33], v[154:155] op_sel_hi:[1,0]
	v_pk_mul_f32 v[34:35], v[34:35], v[154:155] op_sel_hi:[1,0]
	v_pk_mul_f32 v[40:41], v[32:33], v[40:41]
	v_pk_mul_f32 v[32:33], v[42:43], v[46:47]
	v_pk_mul_f32 v[28:29], v[28:29], v[150:151] op_sel_hi:[1,0]
	v_pk_mul_f32 v[42:43], v[34:35], v[32:33]
	v_cvt_pk_bf16_f32 v32, v36, v37
	v_mad_i64_i32 v[36:37], s[6:7], v144, s59, v[112:113]
	v_cvt_pk_bf16_f32 v33, v38, v39
	v_cvt_pk_bf16_f32 v34, v40, v41
	v_cvt_pk_bf16_f32 v35, v42, v43
	v_lshl_add_u64 v[36:37], v[36:37], 0, v[114:115]
	v_mul_f32_e32 v38, 0xbfb8aa3b, v28
	v_mul_f32_e32 v39, 0xbfb8aa3b, v29
; #define PG8_GAS __attribute__((address_space(1)))
; __device__ __forceinline__ unsigned pk2_(float lo, float hi) { f32x2c_t v = {lo, hi}; bf16x2c_t b = __builtin_convertvector(v, bf16x2c_t); return __builtin_bit_cast(unsigned, b); }
; __device__ __forceinline__ float silu_f(float x) { return x * __builtin_amdgcn_rcpf(1.0f + __builtin_amdgcn_exp2f(-1.4426950408889634f * x)); }
;     __device__ __forceinline__ void operator()(const f32x4 (&acc)[2][2][4][2], const Unit& u, int wr, int wc, int fr, int fq) const {
;     ...
;             for (int m = 0; m < 4; ++m) {
;                 const int r = row0 + ai * HALF + m * 16; const float s = rs8[ai][m];
;                 float o[8];
; #pragma unroll
;                 for (int n = 0; n < 2; ++n)
; #pragma unroll
;                     for (int i = 0; i < 4; ++i) o[4 * n + i] = silu_f(acc[ai][0][m][n][i] * s) * (acc[ai][1][m][n][i] * s);
;                 u32x4 w; w.x = pk2_(o[0], o[1]); w.y = pk2_(o[2], o[3]); w.z = pk2_(o[4], o[5]); w.w = pk2_(o[6], o[7]);
;                 *(PG8_GAS u32x4*)(O + (size_t)r * 2816 + col0) = w;
	v_pk_mul_f32 v[30:31], v[30:31], v[150:151] op_sel_hi:[1,0]
	v_exp_f32_e32 v38, v38
	v_exp_f32_e32 v39, v39
	global_store_dwordx4 v[36:37], v[32:35], off
	v_pk_mul_f32 v[20:21], v[20:21], v[150:151] op_sel_hi:[1,0]
	v_pk_mul_f32 v[24:25], v[24:25], v[150:151] op_sel_hi:[1,0]
	v_mul_f32_e32 v34, 0xbfb8aa3b, v30
	v_mul_f32_e32 v35, 0xbfb8aa3b, v31
	v_exp_f32_e32 v34, v34
	v_exp_f32_e32 v35, v35
	v_add_f32_e32 v32, 1.0, v38
	v_add_f32_e32 v33, 1.0, v39
	v_rcp_f32_e32 v32, v32
	v_rcp_f32_e32 v33, v33
	v_add_f32_e32 v34, 1.0, v34
	v_add_f32_e32 v35, 1.0, v35
	v_rcp_f32_e32 v34, v34
	v_rcp_f32_e32 v35, v35
	v_pk_mul_f32 v[28:29], v[28:29], v[32:33]
	v_pk_mul_f32 v[22:23], v[22:23], v[150:151] op_sel_hi:[1,0]
	v_pk_mul_f32 v[20:21], v[20:21], v[28:29]
	v_pk_mul_f32 v[28:29], v[30:31], v[34:35]
	v_mul_f32_e32 v30, 0xbfb8aa3b, v24
	v_mul_f32_e32 v31, 0xbfb8aa3b, v25
	v_exp_f32_e32 v30, v30
	v_exp_f32_e32 v31, v31
	v_pk_mul_f32 v[26:27], v[26:27], v[150:151] op_sel_hi:[1,0]
	v_pk_mul_f32 v[22:23], v[22:23], v[28:29]
	v_add_f32_e32 v28, 1.0, v30
	v_add_f32_e32 v29, 1.0, v31
	v_mul_f32_e32 v30, 0xbfb8aa3b, v26
	v_mul_f32_e32 v31, 0xbfb8aa3b, v27
	v_exp_f32_e32 v30, v30
	v_exp_f32_e32 v31, v31
	v_rcp_f32_e32 v28, v28
	v_rcp_f32_e32 v29, v29
	v_add_f32_e32 v30, 1.0, v30
	v_add_f32_e32 v31, 1.0, v31
	v_rcp_f32_e32 v30, v30
	v_rcp_f32_e32 v31, v31
	v_pk_mul_f32 v[24:25], v[24:25], v[28:29]
	v_pk_mul_f32 v[16:17], v[16:17], v[150:151] op_sel_hi:[1,0]
	v_pk_mul_f32 v[18:19], v[18:19], v[150:151] op_sel_hi:[1,0]
	v_pk_mul_f32 v[24:25], v[16:17], v[24:25]
	v_pk_mul_f32 v[16:17], v[26:27], v[30:31]
	v_pk_mul_f32 v[12:13], v[12:13], v[132:133] op_sel_hi:[1,0]
	v_pk_mul_f32 v[26:27], v[18:19], v[16:17]
	v_cvt_pk_bf16_f32 v16, v20, v21
	v_mad_i64_i32 v[20:21], s[6:7], v142, s59, v[112:113]
	v_cvt_pk_bf16_f32 v17, v22, v23
	v_cvt_pk_bf16_f32 v18, v24, v25
	v_cvt_pk_bf16_f32 v19, v26, v27
	v_lshl_add_u64 v[20:21], v[20:21], 0, v[114:115]
	v_mul_f32_e32 v22, 0xbfb8aa3b, v12
	v_mul_f32_e32 v23, 0xbfb8aa3b, v13
	v_pk_mul_f32 v[14:15], v[14:15], v[132:133] op_sel_hi:[1,0]
	v_exp_f32_e32 v22, v22
	v_exp_f32_e32 v23, v23
	global_store_dwordx4 v[20:21], v[16:19], off
	v_pk_mul_f32 v[4:5], v[4:5], v[132:133] op_sel_hi:[1,0]
	v_pk_mul_f32 v[8:9], v[8:9], v[132:133] op_sel_hi:[1,0]
	v_mul_f32_e32 v18, 0xbfb8aa3b, v14
	v_mul_f32_e32 v19, 0xbfb8aa3b, v15
	v_exp_f32_e32 v18, v18
	v_exp_f32_e32 v19, v19
	v_add_f32_e32 v16, 1.0, v22
	v_add_f32_e32 v17, 1.0, v23
	v_rcp_f32_e32 v16, v16
	v_rcp_f32_e32 v17, v17
	v_add_f32_e32 v18, 1.0, v18
	v_add_f32_e32 v19, 1.0, v19
	v_rcp_f32_e32 v18, v18
	v_rcp_f32_e32 v19, v19
	v_pk_mul_f32 v[12:13], v[12:13], v[16:17]
	v_pk_mul_f32 v[6:7], v[6:7], v[132:133] op_sel_hi:[1,0]
	v_pk_mul_f32 v[4:5], v[4:5], v[12:13]
	v_pk_mul_f32 v[12:13], v[14:15], v[18:19]
	v_mul_f32_e32 v14, 0xbfb8aa3b, v8
	v_mul_f32_e32 v15, 0xbfb8aa3b, v9
	v_exp_f32_e32 v14, v14
	v_exp_f32_e32 v15, v15
	v_pk_mul_f32 v[10:11], v[10:11], v[132:133] op_sel_hi:[1,0]
	v_pk_mul_f32 v[6:7], v[6:7], v[12:13]
	v_add_f32_e32 v12, 1.0, v14
	v_add_f32_e32 v13, 1.0, v15
	v_mul_f32_e32 v14, 0xbfb8aa3b, v10
	v_mul_f32_e32 v15, 0xbfb8aa3b, v11
	v_exp_f32_e32 v14, v14
	v_exp_f32_e32 v15, v15
	v_rcp_f32_e32 v12, v12
	v_rcp_f32_e32 v13, v13
	v_add_f32_e32 v14, 1.0, v14
	v_add_f32_e32 v15, 1.0, v15
	v_rcp_f32_e32 v14, v14
	v_rcp_f32_e32 v15, v15
	v_pk_mul_f32 v[8:9], v[8:9], v[12:13]
	v_pk_mul_f32 v[0:1], v[0:1], v[132:133] op_sel_hi:[1,0]
	v_pk_mul_f32 v[2:3], v[2:3], v[132:133] op_sel_hi:[1,0]
	v_pk_mul_f32 v[8:9], v[0:1], v[8:9]
	v_pk_mul_f32 v[0:1], v[10:11], v[14:15]
	s_andn2_b64 vcc, exec, s[4:5]
	v_pk_mul_f32 v[10:11], v[2:3], v[0:1]
	v_cvt_pk_bf16_f32 v0, v4, v5
	v_mad_i64_i32 v[4:5], s[6:7], v140, s59, v[112:113]
	v_cvt_pk_bf16_f32 v1, v6, v7
	v_cvt_pk_bf16_f32 v2, v8, v9
	v_cvt_pk_bf16_f32 v3, v10, v11
	v_lshl_add_u64 v[4:5], v[4:5], 0, v[114:115]
	s_mov_b64 s[4:5], -1
	global_store_dwordx4 v[4:5], v[0:3], off
	s_cbranch_vccnz .LBB0_690
	s_andn2_b64 vcc, exec, s[12:13]
	s_cbranch_vccnz .LBB0_689
	s_barrier
	s_branch .LBB0_689

; #define PG8_GAS __attribute__((address_space(1)))
; __device__ __forceinline__ unsigned pk2_(float lo, float hi) { f32x2c_t v = {lo, hi}; bf16x2c_t b = __builtin_convertvector(v, bf16x2c_t); return __builtin_bit_cast(unsigned, b); }
;     __device__ __forceinline__ void operator()(const f32x4 (&acc)[2][2][4][2], const Unit& u, int wr, int wc, int fr, int fq) const {
;         const int row0 = u.pm * BM + wr * 64 + fr, col0 = u.pn * BM + wc * 32 + 8 * fq;
;         float rs8[2][4];
; #pragma unroll
;         for (int ai = 0; ai < 2; ++ai)
; #pragma unroll
;             for (int m = 0; m < 4; ++m) { const int r = row0 + ai * HALF + m * 16; rs8[ai][m] = MODE == 0 ? row_rstd(sc, r, fq) : (MODE == 1 ? ((const PG8_GAS float*)sc)[r] : 1.f); }
;         f32x4 cs[2][2];
;         if (MODE == 2) {
; #pragma unroll
;             for (int bj = 0; bj < 2; ++bj)
; #pragma unroll
;                 for (int n = 0; n < 2; ++n) cs[bj][n] = *(const PG8_GAS f32x4*)(sc + col0 + bj * HALF + 4 * n);
;         }
; #pragma unroll
;         for (int ai = 0; ai < 2; ++ai)
; #pragma unroll
;             for (int m = 0; m < 4; ++m) {
;                 const int r = row0 + ai * HALF + m * 16;
;                 const float s = rs8[ai][m];
; #pragma unroll
;                 for (int bj = 0; bj < 2; ++bj) {
;                     f32x4 v0 = acc[ai][bj][m][0], v1 = acc[ai][bj][m][1];
;                     if (MODE == 2) { v0 = v0 * cs[bj][0]; v1 = v1 * cs[bj][1]; } else { v0 = v0 * s; v1 = v1 * s; }
;                     u32x4 w; w.x = pk2_(v0[0], v0[1]); w.y = pk2_(v0[2], v0[3]); w.z = pk2_(v1[0], v1[1]); w.w = pk2_(v1[2], v1[3]);
;                     *(PG8_GAS u32x4*)(O + (size_t)r * ldc + col0 + bj * HALF) = w;
;                 }
;             }
.LBB0_847:
	s_lshl_b32 s8, s8, 8
	v_mov_b32_e32 v132, v252
	s_add_i32 s8, s8, s55
	s_sub_i32 s99, s8, s55
	s_mov_b32 s98, s55
	s_lshl_b32 s100, s99, 6
	s_add_u32 s100, s16, s100
	s_addc_u32 s101, s17, 0
	v_lshrrev_b32_e32 v166, 6, v252
	v_and_b32_e32 v141, 63, v252
	v_lshlrev_b32_e32 v141, 4, v141
	v_lshl_or_b32 v141, v166, 11, v141
	global_load_dwordx4 v[178:181], v141, s[100:101]
	global_load_dwordx4 v[182:185], v141, s[100:101] offset:1024
	v_bfe_u32 v196, v132, 4, 2
	v_and_or_b32 v152, v132, 15, s8
	v_lshlrev_b32_e32 v132, 4, v196
	v_ashrrev_i32_e32 v153, 31, v152
	v_or_b32_e32 v150, 16, v152
	v_lshl_add_u64 v[186:187], s[16:17], 0, v[132:133]
	v_ashrrev_i32_e32 v151, 31, v150
	v_or_b32_e32 v154, 32, v152
	v_ashrrev_i32_e32 v155, 31, v154
	v_or_b32_e32 v146, 48, v152
	v_ashrrev_i32_e32 v147, 31, v146
	v_add_u32_e32 v148, 0x80, v152
	v_ashrrev_i32_e32 v149, 31, v148
	v_add_u32_e32 v142, 0x90, v152
	v_and_b32_e32 v140, 64, v161
	v_add_u32_e32 v147, 64, v140
	v_add_u32_e32 v144, 0xa0, v152
	v_add_u32_e32 v140, 0xb0, v152
	v_ashrrev_i32_e32 v145, 31, v144
	v_xor_b32_e32 v132, 16, v161
	v_cmp_lt_i32_e32 vcc, v132, v147
	v_xor_b32_e32 v143, 32, v161
	s_nop 0
	v_cndmask_b32_e32 v132, v161, v132, vcc
	v_lshlrev_b32_e32 v132, 2, v132
	v_cmp_lt_i32_e32 vcc, v143, v147
	v_mov_b64_e32 v[170:171], s[30:31]
	s_waitcnt vmcnt(0)
	v_add_f32_e32 v178, v178, v179
	v_add_f32_e32 v180, v180, v181
	v_add_f32_e32 v182, v182, v183
	v_add_f32_e32 v184, v184, v185
	v_add_f32_e32 v178, v178, v180
	v_add_f32_e32 v182, v182, v184
	v_mov_b32_e32 v180, 0x358637bd
	s_nop 0
	v_add_f32_dpp v179, v178, v178 quad_perm:[1,0,3,2] row_mask:0xf bank_mask:0xf
	v_add_f32_dpp v183, v182, v182 quad_perm:[1,0,3,2] row_mask:0xf bank_mask:0xf
	v_and_b32_e32 v181, 60, v252
	v_lshl_add_u32 v181, v166, 7, v181
	v_add_f32_dpp v178, v179, v179 quad_perm:[2,3,0,1] row_mask:0xf bank_mask:0xf
	v_add_f32_dpp v182, v183, v183 quad_perm:[2,3,0,1] row_mask:0xf bank_mask:0xf
	v_add_u32_e32 v181, 0x21000, v181
	v_and_b32_e32 v184, 15, v252
	v_fmamk_f32 v178, v178, 0x3a800000, v180
	v_fmamk_f32 v182, v182, 0x3a800000, v180
	v_add_u32_e32 v184, s98, v184
	v_rsq_f32_e32 v178, v178
	v_rsq_f32_e32 v182, v182
	v_lshlrev_b32_e32 v184, 2, v184
	v_add_u32_e32 v184, 0x21000, v184
	ds_write_b32 v181, v178
	ds_write_b32 v181, v182 offset:64
	s_waitcnt lgkmcnt(0)
	s_barrier
	ds_read_b32 v162, v184
	ds_read_b32 v168, v184 offset:64
	ds_read_b32 v172, v184 offset:128
	ds_read_b32 v174, v184 offset:192
	ds_read_b32 v176, v184 offset:512
	ds_read_b32 v164, v184 offset:576
	ds_read_b32 v156, v184 offset:640
	ds_read_b32 v132, v184 offset:704
	s_waitcnt lgkmcnt(0)
	s_lshl_b32 s8, s62, 8
	v_lshl_or_b32 v141, v196, 3, s8
	v_or_b32_e32 v166, s56, v141
	v_pk_mul_f32 v[126:127], v[126:127], v[162:163] op_sel_hi:[1,0]
	v_pk_mul_f32 v[124:125], v[124:125], v[162:163] op_sel_hi:[1,0]
	v_pk_mul_f32 v[120:121], v[120:121], v[162:163] op_sel_hi:[1,0]
	v_ashrrev_i32_e32 v167, 31, v166
	v_pk_mul_f32 v[122:123], v[122:123], v[162:163] op_sel_hi:[1,0]
	v_cvt_pk_bf16_f32 v124, v124, v125
	v_cvt_pk_bf16_f32 v125, v126, v127
	v_cvt_pk_bf16_f32 v126, v120, v121
	v_mov_b64_e32 v[120:121], s[14:15]
	v_cvt_pk_bf16_f32 v127, v122, v123
	v_mad_i64_i32 v[152:153], s[8:9], v152, s61, v[120:121]
	v_lshlrev_b64 v[122:123], 1, v[166:167]
	v_lshl_add_u64 v[152:153], v[152:153], 0, v[122:123]
	global_store_dwordx4 v[152:153], v[124:127], off
	v_pk_mul_f32 v[114:115], v[114:115], v[162:163] op_sel_hi:[1,0]
	v_pk_mul_f32 v[112:113], v[112:113], v[162:163] op_sel_hi:[1,0]
	v_pk_mul_f32 v[124:125], v[106:107], v[162:163] op_sel_hi:[1,0]
	v_pk_mul_f32 v[106:107], v[104:105], v[162:163] op_sel_hi:[1,0]
	v_cvt_pk_bf16_f32 v104, v112, v113
	v_cvt_pk_bf16_f32 v105, v114, v115
	v_cvt_pk_bf16_f32 v106, v106, v107
	v_cvt_pk_bf16_f32 v107, v124, v125
	global_store_dwordx4 v[152:153], v[104:107], off offset:256
	v_pk_mul_f32 v[108:109], v[108:109], v[168:169] op_sel_hi:[1,0]
	v_pk_mul_f32 v[110:111], v[110:111], v[168:169] op_sel_hi:[1,0]
	v_pk_mul_f32 v[106:107], v[118:119], v[168:169] op_sel_hi:[1,0]
	v_pk_mul_f32 v[104:105], v[116:117], v[168:169] op_sel_hi:[1,0]
	v_pk_mul_f32 v[98:99], v[98:99], v[168:169] op_sel_hi:[1,0]
	v_cvt_pk_bf16_f32 v104, v104, v105
	v_cvt_pk_bf16_f32 v105, v106, v107
	v_cvt_pk_bf16_f32 v106, v108, v109
	v_mad_i64_i32 v[108:109], s[8:9], v150, s61, v[120:121]
	v_cvt_pk_bf16_f32 v107, v110, v111
	v_lshl_add_u64 v[108:109], v[108:109], 0, v[122:123]
	global_store_dwordx4 v[108:109], v[104:107], off
	v_pk_mul_f32 v[96:97], v[96:97], v[168:169] op_sel_hi:[1,0]
	v_pk_mul_f32 v[92:93], v[92:93], v[172:173] op_sel_hi:[1,0]
	v_pk_mul_f32 v[104:105], v[90:91], v[168:169] op_sel_hi:[1,0]
	v_pk_mul_f32 v[90:91], v[88:89], v[168:169] op_sel_hi:[1,0]
	v_cvt_pk_bf16_f32 v88, v96, v97
	v_cvt_pk_bf16_f32 v89, v98, v99
	v_cvt_pk_bf16_f32 v90, v90, v91
	v_cvt_pk_bf16_f32 v91, v104, v105
	global_store_dwordx4 v[108:109], v[88:91], off offset:256
	v_pk_mul_f32 v[94:95], v[94:95], v[172:173] op_sel_hi:[1,0]
	v_pk_mul_f32 v[82:83], v[82:83], v[172:173] op_sel_hi:[1,0]
	v_pk_mul_f32 v[90:91], v[102:103], v[172:173] op_sel_hi:[1,0]
	v_pk_mul_f32 v[88:89], v[100:101], v[172:173] op_sel_hi:[1,0]
	v_pk_mul_f32 v[80:81], v[80:81], v[172:173] op_sel_hi:[1,0]
	v_cvt_pk_bf16_f32 v88, v88, v89
	v_cvt_pk_bf16_f32 v89, v90, v91
	v_cvt_pk_bf16_f32 v90, v92, v93
	v_mad_i64_i32 v[92:93], s[8:9], v154, s61, v[120:121]
; #define PG8_GAS __attribute__((address_space(1)))
; __device__ __forceinline__ unsigned pk2_(float lo, float hi) { f32x2c_t v = {lo, hi}; bf16x2c_t b = __builtin_convertvector(v, bf16x2c_t); return __builtin_bit_cast(unsigned, b); }
;     __device__ __forceinline__ void operator()(const f32x4 (&acc)[2][2][4][2], const Unit& u, int wr, int wc, int fr, int fq) const {
;     ...
; #pragma unroll
;         for (int ai = 0; ai < 2; ++ai)
; #pragma unroll
;             for (int m = 0; m < 4; ++m) {
;                 const int r = row0 + ai * HALF + m * 16;
;                 const float s = rs8[ai][m];
; #pragma unroll
;                 for (int bj = 0; bj < 2; ++bj) {
;                     f32x4 v0 = acc[ai][bj][m][0], v1 = acc[ai][bj][m][1];
;                     if (MODE == 2) { v0 = v0 * cs[bj][0]; v1 = v1 * cs[bj][1]; } else { v0 = v0 * s; v1 = v1 * s; }
;                     u32x4 w; w.x = pk2_(v0[0], v0[1]); w.y = pk2_(v0[2], v0[3]); w.z = pk2_(v1[0], v1[1]); w.w = pk2_(v1[2], v1[3]);
;                     *(PG8_GAS u32x4*)(O + (size_t)r * ldc + col0 + bj * HALF) = w;
;                 }
;             }
	v_cvt_pk_bf16_f32 v91, v94, v95
	v_lshl_add_u64 v[92:93], v[92:93], 0, v[122:123]
	global_store_dwordx4 v[92:93], v[88:91], off
	v_pk_mul_f32 v[76:77], v[76:77], v[174:175] op_sel_hi:[1,0]
	v_pk_mul_f32 v[78:79], v[78:79], v[174:175] op_sel_hi:[1,0]
	v_pk_mul_f32 v[88:89], v[74:75], v[172:173] op_sel_hi:[1,0]
	v_pk_mul_f32 v[74:75], v[72:73], v[172:173] op_sel_hi:[1,0]
	v_cvt_pk_bf16_f32 v72, v80, v81
	v_cvt_pk_bf16_f32 v73, v82, v83
	v_cvt_pk_bf16_f32 v74, v74, v75
	v_cvt_pk_bf16_f32 v75, v88, v89
	global_store_dwordx4 v[92:93], v[72:75], off offset:256
	v_pk_mul_f32 v[70:71], v[70:71], v[174:175] op_sel_hi:[1,0]
	v_pk_mul_f32 v[68:69], v[68:69], v[174:175] op_sel_hi:[1,0]
	v_pk_mul_f32 v[74:75], v[86:87], v[174:175] op_sel_hi:[1,0]
	v_pk_mul_f32 v[72:73], v[84:85], v[174:175] op_sel_hi:[1,0]
	v_pk_mul_f32 v[60:61], v[60:61], v[176:177] op_sel_hi:[1,0]
	v_cvt_pk_bf16_f32 v72, v72, v73
	v_cvt_pk_bf16_f32 v73, v74, v75
	v_cvt_pk_bf16_f32 v74, v76, v77
	v_mad_i64_i32 v[76:77], s[8:9], v146, s61, v[120:121]
	v_cvt_pk_bf16_f32 v75, v78, v79
	v_lshl_add_u64 v[76:77], v[76:77], 0, v[122:123]
	global_store_dwordx4 v[76:77], v[72:75], off
	v_pk_mul_f32 v[62:63], v[62:63], v[176:177] op_sel_hi:[1,0]
	v_pk_mul_f32 v[50:51], v[50:51], v[176:177] op_sel_hi:[1,0]
	v_pk_mul_f32 v[72:73], v[66:67], v[174:175] op_sel_hi:[1,0]
	v_pk_mul_f32 v[66:67], v[64:65], v[174:175] op_sel_hi:[1,0]
	v_cvt_pk_bf16_f32 v64, v68, v69
	v_cvt_pk_bf16_f32 v65, v70, v71
	v_cvt_pk_bf16_f32 v66, v66, v67
	v_cvt_pk_bf16_f32 v67, v72, v73
	global_store_dwordx4 v[76:77], v[64:67], off offset:256
	v_pk_mul_f32 v[48:49], v[48:49], v[176:177] op_sel_hi:[1,0]
	v_pk_mul_f32 v[44:45], v[44:45], v[164:165] op_sel_hi:[1,0]
	v_pk_mul_f32 v[64:65], v[58:59], v[176:177] op_sel_hi:[1,0]
	v_pk_mul_f32 v[58:59], v[56:57], v[176:177] op_sel_hi:[1,0]
	v_cvt_pk_bf16_f32 v56, v60, v61
	v_mad_i64_i32 v[60:61], s[8:9], v148, s61, v[120:121]
	v_cvt_pk_bf16_f32 v57, v62, v63
	v_cvt_pk_bf16_f32 v58, v58, v59
	v_cvt_pk_bf16_f32 v59, v64, v65
	v_lshl_add_u64 v[60:61], v[60:61], 0, v[122:123]
	global_store_dwordx4 v[60:61], v[56:59], off
	v_pk_mul_f32 v[46:47], v[46:47], v[164:165] op_sel_hi:[1,0]
	v_pk_mul_f32 v[34:35], v[34:35], v[164:165] op_sel_hi:[1,0]
	v_pk_mul_f32 v[56:57], v[42:43], v[176:177] op_sel_hi:[1,0]
	v_pk_mul_f32 v[42:43], v[40:41], v[176:177] op_sel_hi:[1,0]
	v_cvt_pk_bf16_f32 v40, v48, v49
	v_cvt_pk_bf16_f32 v41, v50, v51
	v_cvt_pk_bf16_f32 v42, v42, v43
	v_cvt_pk_bf16_f32 v43, v56, v57
	global_store_dwordx4 v[60:61], v[40:43], off offset:256
	v_pk_mul_f32 v[32:33], v[32:33], v[164:165] op_sel_hi:[1,0]
	v_pk_mul_f32 v[28:29], v[28:29], v[156:157] op_sel_hi:[1,0]
	v_pk_mul_f32 v[42:43], v[54:55], v[164:165] op_sel_hi:[1,0]
	v_pk_mul_f32 v[40:41], v[52:53], v[164:165] op_sel_hi:[1,0]
	v_pk_mul_f32 v[30:31], v[30:31], v[156:157] op_sel_hi:[1,0]
	v_cvt_pk_bf16_f32 v40, v40, v41
	v_cvt_pk_bf16_f32 v41, v42, v43
	v_cvt_pk_bf16_f32 v42, v44, v45
	v_mad_i64_i32 v[44:45], s[8:9], v142, s61, v[120:121]
	v_cvt_pk_bf16_f32 v43, v46, v47
	v_lshl_add_u64 v[44:45], v[44:45], 0, v[122:123]
	global_store_dwordx4 v[44:45], v[40:43], off
	v_pk_mul_f32 v[18:19], v[18:19], v[156:157] op_sel_hi:[1,0]
	v_pk_mul_f32 v[16:17], v[16:17], v[156:157] op_sel_hi:[1,0]
	v_pk_mul_f32 v[40:41], v[26:27], v[164:165] op_sel_hi:[1,0]
	v_pk_mul_f32 v[26:27], v[24:25], v[164:165] op_sel_hi:[1,0]
	v_cvt_pk_bf16_f32 v24, v32, v33
	v_cvt_pk_bf16_f32 v25, v34, v35
	v_cvt_pk_bf16_f32 v26, v26, v27
	v_cvt_pk_bf16_f32 v27, v40, v41
	global_store_dwordx4 v[44:45], v[24:27], off offset:256
	v_pk_mul_f32 v[12:13], v[12:13], v[132:133] op_sel_hi:[1,0]
	v_pk_mul_f32 v[14:15], v[14:15], v[132:133] op_sel_hi:[1,0]
	v_pk_mul_f32 v[26:27], v[38:39], v[156:157] op_sel_hi:[1,0]
	v_pk_mul_f32 v[24:25], v[36:37], v[156:157] op_sel_hi:[1,0]
	v_pk_mul_f32 v[6:7], v[6:7], v[132:133] op_sel_hi:[1,0]
	v_cvt_pk_bf16_f32 v24, v24, v25
	v_cvt_pk_bf16_f32 v25, v26, v27
	v_cvt_pk_bf16_f32 v26, v28, v29
	v_mad_i64_i32 v[28:29], s[8:9], v144, s61, v[120:121]
	v_cvt_pk_bf16_f32 v27, v30, v31
	v_lshl_add_u64 v[28:29], v[28:29], 0, v[122:123]
	global_store_dwordx4 v[28:29], v[24:27], off
	v_pk_mul_f32 v[4:5], v[4:5], v[132:133] op_sel_hi:[1,0]
	s_andn2_b64 vcc, exec, s[6:7]
	v_pk_mul_f32 v[24:25], v[10:11], v[156:157] op_sel_hi:[1,0]
	v_pk_mul_f32 v[10:11], v[8:9], v[156:157] op_sel_hi:[1,0]
	v_cvt_pk_bf16_f32 v8, v16, v17
	v_cvt_pk_bf16_f32 v9, v18, v19
	v_cvt_pk_bf16_f32 v10, v10, v11
	v_cvt_pk_bf16_f32 v11, v24, v25
	global_store_dwordx4 v[28:29], v[8:11], off offset:256
	s_mov_b64 s[6:7], -1
	s_nop 0
	v_pk_mul_f32 v[10:11], v[22:23], v[132:133] op_sel_hi:[1,0]
	v_pk_mul_f32 v[8:9], v[20:21], v[132:133] op_sel_hi:[1,0]
	s_nop 0
	v_cvt_pk_bf16_f32 v8, v8, v9
	v_cvt_pk_bf16_f32 v9, v10, v11
	v_cvt_pk_bf16_f32 v10, v12, v13
	v_mad_i64_i32 v[12:13], s[8:9], v140, s61, v[120:121]
	v_cvt_pk_bf16_f32 v11, v14, v15
	v_lshl_add_u64 v[12:13], v[12:13], 0, v[122:123]
	global_store_dwordx4 v[12:13], v[8:11], off
	s_nop 1
	v_pk_mul_f32 v[8:9], v[2:3], v[132:133] op_sel_hi:[1,0]
	v_pk_mul_f32 v[2:3], v[0:1], v[132:133] op_sel_hi:[1,0]
	v_cvt_pk_bf16_f32 v0, v4, v5
	v_cvt_pk_bf16_f32 v1, v6, v7
	v_cvt_pk_bf16_f32 v2, v2, v3
	v_cvt_pk_bf16_f32 v3, v8, v9
	global_store_dwordx4 v[12:13], v[0:3], off offset:256
	s_cbranch_vccnz .LBB0_840
	s_andn2_b64 vcc, exec, s[12:13]
	s_cbranch_vccnz .LBB0_839
	s_barrier
	s_branch .LBB0_839

; #define PG8_GAS __attribute__((address_space(1)))
; __device__ __forceinline__ unsigned pk2_(float lo, float hi) { f32x2c_t v = {lo, hi}; bf16x2c_t b = __builtin_convertvector(v, bf16x2c_t); return __builtin_bit_cast(unsigned, b); }
;     __device__ __forceinline__ void operator()(const f32x4 (&acc)[2][2][4][2], const Unit& u, int wr, int wc, int fr, int fq) const {
;         const int row0 = u.pm * BM + wr * 64 + fr, col0 = u.pn * BM + wc * 32 + 8 * fq;
;         float rs8[2][4];
; #pragma unroll
;         for (int ai = 0; ai < 2; ++ai)
; #pragma unroll
;             for (int m = 0; m < 4; ++m) { const int r = row0 + ai * HALF + m * 16; rs8[ai][m] = MODE == 0 ? row_rstd(sc, r, fq) : (MODE == 1 ? ((const PG8_GAS float*)sc)[r] : 1.f); }
;         f32x4 cs[2][2];
;         if (MODE == 2) {
; #pragma unroll
;             for (int bj = 0; bj < 2; ++bj)
; #pragma unroll
;                 for (int n = 0; n < 2; ++n) cs[bj][n] = *(const PG8_GAS f32x4*)(sc + col0 + bj * HALF + 4 * n);
;         }
; #pragma unroll
;         for (int ai = 0; ai < 2; ++ai)
; #pragma unroll
;             for (int m = 0; m < 4; ++m) {
;                 const int r = row0 + ai * HALF + m * 16;
;                 const float s = rs8[ai][m];
; #pragma unroll
;                 for (int bj = 0; bj < 2; ++bj) {
;                     f32x4 v0 = acc[ai][bj][m][0], v1 = acc[ai][bj][m][1];
;                     if (MODE == 2) { v0 = v0 * cs[bj][0]; v1 = v1 * cs[bj][1]; } else { v0 = v0 * s; v1 = v1 * s; }
;                     u32x4 w; w.x = pk2_(v0[0], v0[1]); w.y = pk2_(v0[2], v0[3]); w.z = pk2_(v1[0], v1[1]); w.w = pk2_(v1[2], v1[3]);
;                     *(PG8_GAS u32x4*)(O + (size_t)r * ldc + col0 + bj * HALF) = w;
;                 }
;             }
.LBB0_1462:
	s_lshl_b32 s8, s8, 8
	v_mov_b32_e32 v132, v252
	s_add_i32 s8, s8, s55
	s_sub_i32 s99, s8, s55
	s_mov_b32 s98, s55
	s_lshl_b32 s100, s99, 6
	s_add_u32 s100, s16, s100
	s_addc_u32 s101, s17, 0
	v_lshrrev_b32_e32 v167, 6, v252
	v_and_b32_e32 v166, 63, v252
	v_lshlrev_b32_e32 v166, 4, v166
	v_lshl_or_b32 v166, v167, 11, v166
	global_load_dwordx4 v[176:179], v166, s[100:101]
	global_load_dwordx4 v[180:183], v166, s[100:101] offset:1024
	v_cmp_lt_i32_e32 vcc, v227, v226
	v_bfe_u32 v161, v132, 4, 2
	v_and_or_b32 v154, v132, 15, s8
	v_lshlrev_b32_e32 v132, 4, v161
	v_ashrrev_i32_e32 v155, 31, v154
	v_or_b32_e32 v150, 16, v154
	v_lshl_add_u64 v[186:187], s[16:17], 0, v[132:133]
	v_ashrrev_i32_e32 v151, 31, v150
	v_or_b32_e32 v152, 32, v154
	v_ashrrev_i32_e32 v153, 31, v152
	v_or_b32_e32 v146, 48, v154
	v_ashrrev_i32_e32 v147, 31, v146
	v_add_u32_e32 v148, 0x80, v154
	v_ashrrev_i32_e32 v149, 31, v148
	v_add_u32_e32 v142, 0x90, v154
	v_ashrrev_i32_e32 v143, 31, v142
	v_add_u32_e32 v144, 0xa0, v154
	v_add_u32_e32 v140, 0xb0, v154
	v_ashrrev_i32_e32 v145, 31, v144
	v_ashrrev_i32_e32 v141, 31, v140
	v_cndmask_b32_e32 v132, v253, v227, vcc
	v_lshlrev_b32_e32 v132, 2, v132
	v_xor_b32_e32 v156, 32, v253
	v_cmp_lt_i32_e32 vcc, v156, v226
	v_mov_b64_e32 v[194:195], s[30:31]
	s_nop 0
	v_cndmask_b32_e32 v156, v253, v156, vcc
	v_lshlrev_b32_e32 v156, 2, v156
	s_waitcnt vmcnt(0)
	v_add_f32_e32 v176, v176, v177
	v_add_f32_e32 v178, v178, v179
	v_add_f32_e32 v180, v180, v181
	v_add_f32_e32 v182, v182, v183
	v_add_f32_e32 v176, v176, v178
	v_add_f32_e32 v180, v180, v182
	v_mov_b32_e32 v178, 0x358637bd
	s_nop 0
	v_add_f32_dpp v177, v176, v176 quad_perm:[1,0,3,2] row_mask:0xf bank_mask:0xf
	v_add_f32_dpp v181, v180, v180 quad_perm:[1,0,3,2] row_mask:0xf bank_mask:0xf
	v_and_b32_e32 v179, 60, v252
	v_lshl_add_u32 v179, v167, 7, v179
	v_add_f32_dpp v176, v177, v177 quad_perm:[2,3,0,1] row_mask:0xf bank_mask:0xf
	v_add_f32_dpp v180, v181, v181 quad_perm:[2,3,0,1] row_mask:0xf bank_mask:0xf
	v_add_u32_e32 v179, 0x21000, v179
	v_and_b32_e32 v182, 15, v252
	v_fmamk_f32 v176, v176, 0x3a800000, v178
	v_fmamk_f32 v180, v180, 0x3a800000, v178
	v_add_u32_e32 v182, s98, v182
	v_rsq_f32_e32 v176, v176
	v_rsq_f32_e32 v180, v180
	v_lshlrev_b32_e32 v182, 2, v182
	v_add_u32_e32 v182, 0x21000, v182
	ds_write_b32 v179, v176
	ds_write_b32 v179, v180 offset:64
	s_waitcnt lgkmcnt(0)
	s_barrier
	ds_read_b32 v162, v182
	ds_read_b32 v168, v182 offset:64
	ds_read_b32 v170, v182 offset:128
	ds_read_b32 v172, v182 offset:192
	ds_read_b32 v174, v182 offset:512
	ds_read_b32 v164, v182 offset:576
	ds_read_b32 v156, v182 offset:640
	ds_read_b32 v132, v182 offset:704
	s_waitcnt lgkmcnt(0)
	v_pk_mul_f32 v[108:109], v[108:109], v[168:169] op_sel_hi:[1,0]
	s_lshl_b32 s8, s61, 8
	v_lshl_or_b32 v161, v161, 3, s8
	v_or_b32_e32 v166, s56, v161
	v_pk_mul_f32 v[124:125], v[124:125], v[162:163] op_sel_hi:[1,0]
	v_pk_mul_f32 v[120:121], v[120:121], v[162:163] op_sel_hi:[1,0]
	v_ashrrev_i32_e32 v167, 31, v166
	v_pk_mul_f32 v[126:127], v[126:127], v[162:163] op_sel_hi:[1,0]
	v_pk_mul_f32 v[176:177], v[122:123], v[162:163] op_sel_hi:[1,0]
	v_cvt_pk_bf16_f32 v122, v124, v125
	v_cvt_pk_bf16_f32 v124, v120, v121
	v_lshlrev_b64 v[120:121], 11, v[154:155]
	v_cvt_pk_bf16_f32 v123, v126, v127
	v_lshl_add_u64 v[126:127], s[14:15], 0, v[120:121]
	v_lshlrev_b64 v[120:121], 1, v[166:167]
	v_cvt_pk_bf16_f32 v125, v176, v177
	v_lshl_add_u64 v[126:127], v[126:127], 0, v[120:121]
	global_store_dwordx4 v[126:127], v[122:125], off
	v_pk_mul_f32 v[114:115], v[114:115], v[162:163] op_sel_hi:[1,0]
	v_pk_mul_f32 v[112:113], v[112:113], v[162:163] op_sel_hi:[1,0]
	v_pk_mul_f32 v[122:123], v[106:107], v[162:163] op_sel_hi:[1,0]
	v_pk_mul_f32 v[106:107], v[104:105], v[162:163] op_sel_hi:[1,0]
	v_cvt_pk_bf16_f32 v104, v112, v113
	v_cvt_pk_bf16_f32 v105, v114, v115
	v_cvt_pk_bf16_f32 v106, v106, v107
	v_cvt_pk_bf16_f32 v107, v122, v123
	global_store_dwordx4 v[126:127], v[104:107], off offset:256
	v_pk_mul_f32 v[110:111], v[110:111], v[168:169] op_sel_hi:[1,0]
	v_pk_mul_f32 v[98:99], v[98:99], v[168:169] op_sel_hi:[1,0]
	v_pk_mul_f32 v[106:107], v[118:119], v[168:169] op_sel_hi:[1,0]
	v_pk_mul_f32 v[104:105], v[116:117], v[168:169] op_sel_hi:[1,0]
	v_pk_mul_f32 v[96:97], v[96:97], v[168:169] op_sel_hi:[1,0]
	v_cvt_pk_bf16_f32 v104, v104, v105
	v_cvt_pk_bf16_f32 v105, v106, v107
	v_cvt_pk_bf16_f32 v106, v108, v109
	v_lshlrev_b64 v[108:109], 11, v[150:151]
	v_lshl_add_u64 v[108:109], s[14:15], 0, v[108:109]
	v_cvt_pk_bf16_f32 v107, v110, v111
	v_lshl_add_u64 v[108:109], v[108:109], 0, v[120:121]
	global_store_dwordx4 v[108:109], v[104:107], off
	v_pk_mul_f32 v[92:93], v[92:93], v[170:171] op_sel_hi:[1,0]
	v_pk_mul_f32 v[94:95], v[94:95], v[170:171] op_sel_hi:[1,0]
	v_pk_mul_f32 v[104:105], v[90:91], v[168:169] op_sel_hi:[1,0]
	v_pk_mul_f32 v[90:91], v[88:89], v[168:169] op_sel_hi:[1,0]
	v_cvt_pk_bf16_f32 v88, v96, v97
	v_cvt_pk_bf16_f32 v89, v98, v99
	v_cvt_pk_bf16_f32 v90, v90, v91
	v_cvt_pk_bf16_f32 v91, v104, v105
	global_store_dwordx4 v[108:109], v[88:91], off offset:256
	v_pk_mul_f32 v[82:83], v[82:83], v[170:171] op_sel_hi:[1,0]
	v_pk_mul_f32 v[80:81], v[80:81], v[170:171] op_sel_hi:[1,0]
	v_pk_mul_f32 v[90:91], v[102:103], v[170:171] op_sel_hi:[1,0]
	v_pk_mul_f32 v[88:89], v[100:101], v[170:171] op_sel_hi:[1,0]
	v_pk_mul_f32 v[76:77], v[76:77], v[172:173] op_sel_hi:[1,0]
	v_cvt_pk_bf16_f32 v88, v88, v89
	v_cvt_pk_bf16_f32 v89, v90, v91
	v_cvt_pk_bf16_f32 v90, v92, v93
	v_lshlrev_b64 v[92:93], 11, v[152:153]
; #define PG8_GAS __attribute__((address_space(1)))
; __device__ __forceinline__ unsigned pk2_(float lo, float hi) { f32x2c_t v = {lo, hi}; bf16x2c_t b = __builtin_convertvector(v, bf16x2c_t); return __builtin_bit_cast(unsigned, b); }
;     __device__ __forceinline__ void operator()(const f32x4 (&acc)[2][2][4][2], const Unit& u, int wr, int wc, int fr, int fq) const {
;     ...
; #pragma unroll
;         for (int ai = 0; ai < 2; ++ai)
; #pragma unroll
;             for (int m = 0; m < 4; ++m) {
;                 const int r = row0 + ai * HALF + m * 16;
;                 const float s = rs8[ai][m];
; #pragma unroll
;                 for (int bj = 0; bj < 2; ++bj) {
;                     f32x4 v0 = acc[ai][bj][m][0], v1 = acc[ai][bj][m][1];
;                     if (MODE == 2) { v0 = v0 * cs[bj][0]; v1 = v1 * cs[bj][1]; } else { v0 = v0 * s; v1 = v1 * s; }
;                     u32x4 w; w.x = pk2_(v0[0], v0[1]); w.y = pk2_(v0[2], v0[3]); w.z = pk2_(v1[0], v1[1]); w.w = pk2_(v1[2], v1[3]);
;                     *(PG8_GAS u32x4*)(O + (size_t)r * ldc + col0 + bj * HALF) = w;
;                 }
;             }
	v_lshl_add_u64 v[92:93], s[14:15], 0, v[92:93]
	v_cvt_pk_bf16_f32 v91, v94, v95
	v_lshl_add_u64 v[92:93], v[92:93], 0, v[120:121]
	global_store_dwordx4 v[92:93], v[88:91], off
	v_pk_mul_f32 v[78:79], v[78:79], v[172:173] op_sel_hi:[1,0]
	v_pk_mul_f32 v[70:71], v[70:71], v[172:173] op_sel_hi:[1,0]
	v_pk_mul_f32 v[88:89], v[74:75], v[170:171] op_sel_hi:[1,0]
	v_pk_mul_f32 v[74:75], v[72:73], v[170:171] op_sel_hi:[1,0]
	v_cvt_pk_bf16_f32 v72, v80, v81
	v_cvt_pk_bf16_f32 v73, v82, v83
	v_cvt_pk_bf16_f32 v74, v74, v75
	v_cvt_pk_bf16_f32 v75, v88, v89
	global_store_dwordx4 v[92:93], v[72:75], off offset:256
	v_pk_mul_f32 v[68:69], v[68:69], v[172:173] op_sel_hi:[1,0]
	v_pk_mul_f32 v[60:61], v[60:61], v[174:175] op_sel_hi:[1,0]
	v_pk_mul_f32 v[74:75], v[86:87], v[172:173] op_sel_hi:[1,0]
	v_pk_mul_f32 v[72:73], v[84:85], v[172:173] op_sel_hi:[1,0]
	v_pk_mul_f32 v[62:63], v[62:63], v[174:175] op_sel_hi:[1,0]
	v_cvt_pk_bf16_f32 v72, v72, v73
	v_cvt_pk_bf16_f32 v73, v74, v75
	v_cvt_pk_bf16_f32 v74, v76, v77
	v_lshlrev_b64 v[76:77], 11, v[146:147]
	v_lshl_add_u64 v[76:77], s[14:15], 0, v[76:77]
	v_cvt_pk_bf16_f32 v75, v78, v79
	v_lshl_add_u64 v[76:77], v[76:77], 0, v[120:121]
	global_store_dwordx4 v[76:77], v[72:75], off
	v_pk_mul_f32 v[50:51], v[50:51], v[174:175] op_sel_hi:[1,0]
	v_pk_mul_f32 v[48:49], v[48:49], v[174:175] op_sel_hi:[1,0]
	v_pk_mul_f32 v[72:73], v[66:67], v[172:173] op_sel_hi:[1,0]
	v_pk_mul_f32 v[66:67], v[64:65], v[172:173] op_sel_hi:[1,0]
	v_cvt_pk_bf16_f32 v64, v68, v69
	v_cvt_pk_bf16_f32 v65, v70, v71
	v_cvt_pk_bf16_f32 v66, v66, v67
	v_cvt_pk_bf16_f32 v67, v72, v73
	global_store_dwordx4 v[76:77], v[64:67], off offset:256
	v_pk_mul_f32 v[44:45], v[44:45], v[164:165] op_sel_hi:[1,0]
	v_pk_mul_f32 v[46:47], v[46:47], v[164:165] op_sel_hi:[1,0]
	v_pk_mul_f32 v[64:65], v[58:59], v[174:175] op_sel_hi:[1,0]
	v_pk_mul_f32 v[58:59], v[56:57], v[174:175] op_sel_hi:[1,0]
	v_cvt_pk_bf16_f32 v56, v60, v61
	v_lshlrev_b64 v[60:61], 11, v[148:149]
	v_lshl_add_u64 v[60:61], s[14:15], 0, v[60:61]
	v_cvt_pk_bf16_f32 v57, v62, v63
	v_cvt_pk_bf16_f32 v58, v58, v59
	v_cvt_pk_bf16_f32 v59, v64, v65
	v_lshl_add_u64 v[60:61], v[60:61], 0, v[120:121]
	global_store_dwordx4 v[60:61], v[56:59], off
	v_pk_mul_f32 v[34:35], v[34:35], v[164:165] op_sel_hi:[1,0]
	v_pk_mul_f32 v[32:33], v[32:33], v[164:165] op_sel_hi:[1,0]
	v_pk_mul_f32 v[56:57], v[42:43], v[174:175] op_sel_hi:[1,0]
	v_pk_mul_f32 v[42:43], v[40:41], v[174:175] op_sel_hi:[1,0]
	v_cvt_pk_bf16_f32 v40, v48, v49
	v_cvt_pk_bf16_f32 v41, v50, v51
	v_cvt_pk_bf16_f32 v42, v42, v43
	v_cvt_pk_bf16_f32 v43, v56, v57
	global_store_dwordx4 v[60:61], v[40:43], off offset:256
	v_pk_mul_f32 v[28:29], v[28:29], v[156:157] op_sel_hi:[1,0]
	v_pk_mul_f32 v[30:31], v[30:31], v[156:157] op_sel_hi:[1,0]
	v_pk_mul_f32 v[42:43], v[54:55], v[164:165] op_sel_hi:[1,0]
	v_pk_mul_f32 v[40:41], v[52:53], v[164:165] op_sel_hi:[1,0]
	v_pk_mul_f32 v[18:19], v[18:19], v[156:157] op_sel_hi:[1,0]
	v_cvt_pk_bf16_f32 v40, v40, v41
	v_cvt_pk_bf16_f32 v41, v42, v43
	v_cvt_pk_bf16_f32 v42, v44, v45
	v_lshlrev_b64 v[44:45], 11, v[142:143]
	v_lshl_add_u64 v[44:45], s[14:15], 0, v[44:45]
	v_cvt_pk_bf16_f32 v43, v46, v47
	v_lshl_add_u64 v[44:45], v[44:45], 0, v[120:121]
	global_store_dwordx4 v[44:45], v[40:43], off
	v_pk_mul_f32 v[16:17], v[16:17], v[156:157] op_sel_hi:[1,0]
	v_pk_mul_f32 v[12:13], v[12:13], v[132:133] op_sel_hi:[1,0]
	v_pk_mul_f32 v[40:41], v[26:27], v[164:165] op_sel_hi:[1,0]
	v_pk_mul_f32 v[26:27], v[24:25], v[164:165] op_sel_hi:[1,0]
	v_cvt_pk_bf16_f32 v24, v32, v33
	v_cvt_pk_bf16_f32 v25, v34, v35
	v_cvt_pk_bf16_f32 v26, v26, v27
	v_cvt_pk_bf16_f32 v27, v40, v41
	global_store_dwordx4 v[44:45], v[24:27], off offset:256
	v_pk_mul_f32 v[14:15], v[14:15], v[132:133] op_sel_hi:[1,0]
	v_pk_mul_f32 v[6:7], v[6:7], v[132:133] op_sel_hi:[1,0]
	v_pk_mul_f32 v[26:27], v[38:39], v[156:157] op_sel_hi:[1,0]
	v_pk_mul_f32 v[24:25], v[36:37], v[156:157] op_sel_hi:[1,0]
	v_pk_mul_f32 v[4:5], v[4:5], v[132:133] op_sel_hi:[1,0]
	v_cvt_pk_bf16_f32 v24, v24, v25
	v_cvt_pk_bf16_f32 v25, v26, v27
	v_cvt_pk_bf16_f32 v26, v28, v29
	v_lshlrev_b64 v[28:29], 11, v[144:145]
	v_lshl_add_u64 v[28:29], s[14:15], 0, v[28:29]
	v_cvt_pk_bf16_f32 v27, v30, v31
	v_lshl_add_u64 v[28:29], v[28:29], 0, v[120:121]
	global_store_dwordx4 v[28:29], v[24:27], off
	s_andn2_b64 vcc, exec, s[6:7]
	s_mov_b64 s[6:7], -1
	v_pk_mul_f32 v[24:25], v[10:11], v[156:157] op_sel_hi:[1,0]
	v_pk_mul_f32 v[10:11], v[8:9], v[156:157] op_sel_hi:[1,0]
	v_cvt_pk_bf16_f32 v8, v16, v17
	v_cvt_pk_bf16_f32 v9, v18, v19
	v_cvt_pk_bf16_f32 v10, v10, v11
	v_cvt_pk_bf16_f32 v11, v24, v25
	global_store_dwordx4 v[28:29], v[8:11], off offset:256
	s_nop 1
	v_pk_mul_f32 v[10:11], v[22:23], v[132:133] op_sel_hi:[1,0]
	v_pk_mul_f32 v[8:9], v[20:21], v[132:133] op_sel_hi:[1,0]
	s_nop 0
	v_cvt_pk_bf16_f32 v8, v8, v9
	v_cvt_pk_bf16_f32 v9, v10, v11
	v_cvt_pk_bf16_f32 v10, v12, v13
	v_lshlrev_b64 v[12:13], 11, v[140:141]
	v_lshl_add_u64 v[12:13], s[14:15], 0, v[12:13]
	v_cvt_pk_bf16_f32 v11, v14, v15
	v_lshl_add_u64 v[12:13], v[12:13], 0, v[120:121]
	global_store_dwordx4 v[12:13], v[8:11], off
	s_nop 1
	v_pk_mul_f32 v[8:9], v[2:3], v[132:133] op_sel_hi:[1,0]
	v_pk_mul_f32 v[2:3], v[0:1], v[132:133] op_sel_hi:[1,0]
	v_cvt_pk_bf16_f32 v0, v4, v5
	v_cvt_pk_bf16_f32 v1, v6, v7
	v_cvt_pk_bf16_f32 v2, v2, v3
	v_cvt_pk_bf16_f32 v3, v8, v9
	global_store_dwordx4 v[12:13], v[0:3], off offset:256
	s_cbranch_vccnz .LBB0_1451
	s_andn2_b64 vcc, exec, s[12:13]
	s_cbranch_vccnz .LBB0_1450
	s_barrier
	s_branch .LBB0_1450

; #define PG8_GAS __attribute__((address_space(1)))
; __device__ __forceinline__ unsigned pk2_(float lo, float hi) { f32x2c_t v = {lo, hi}; bf16x2c_t b = __builtin_convertvector(v, bf16x2c_t); return __builtin_bit_cast(unsigned, b); }
; __device__ __forceinline__ float row_rstd(const float* parts, int r, int fq) {
;     const f32x4 p = *(const PG8_GAS f32x4*)(parts + (size_t)r * 16 + 4 * fq);
;     float s = (p[0] + p[1]) + (p[2] + p[3]);
;     s += __shfl_xor(s, 16); s += __shfl_xor(s, 32);
;     return rsqrtf(s * (1.0f / 1024.0f) + RMS_EPS);
; }
; __device__ __forceinline__ float silu_f(float x) { return x * __builtin_amdgcn_rcpf(1.0f + __builtin_amdgcn_exp2f(-1.4426950408889634f * x)); }
;     __device__ __forceinline__ void operator()(const f32x4 (&acc)[2][2][4][2], const Unit& u, int wr, int wc, int fr, int fq) const {
;         const int row0 = u.pm * BM + wr * 64 + fr, col0 = u.pn * 128 + wc * 32 + 8 * fq;
;         float rs8[2][4];
; #pragma unroll
;         for (int ai = 0; ai < 2; ++ai)
; #pragma unroll
;             for (int m = 0; m < 4; ++m) rs8[ai][m] = row_rstd(parts, row0 + ai * HALF + m * 16, fq);
; #pragma unroll
;         for (int ai = 0; ai < 2; ++ai)
; #pragma unroll
;             for (int m = 0; m < 4; ++m) {
;                 const int r = row0 + ai * HALF + m * 16; const float s = rs8[ai][m];
;                 float o[8];
; #pragma unroll
;                 for (int n = 0; n < 2; ++n)
; #pragma unroll
;                     for (int i = 0; i < 4; ++i) o[4 * n + i] = silu_f(acc[ai][0][m][n][i] * s) * (acc[ai][1][m][n][i] * s);
;                 u32x4 w; w.x = pk2_(o[0], o[1]); w.y = pk2_(o[2], o[3]); w.z = pk2_(o[4], o[5]); w.w = pk2_(o[6], o[7]);
;                 *(PG8_GAS u32x4*)(O + (size_t)r * 2816 + col0) = w;
.LBB0_1661:
	s_lshl_b32 s8, s8, 8
	v_mov_b32_e32 v132, v252
	s_add_i32 s8, s8, s56
	s_sub_i32 s99, s8, s56
	s_mov_b32 s98, s56
	s_lshl_b32 s100, s99, 6
	s_add_u32 s100, s16, s100
	s_addc_u32 s101, s17, 0
	v_lshrrev_b32_e32 v143, 6, v252
	v_and_b32_e32 v141, 63, v252
	v_lshlrev_b32_e32 v141, 4, v141
	v_lshl_or_b32 v141, v143, 11, v141
	global_load_dwordx4 v[174:177], v141, s[100:101]
	global_load_dwordx4 v[178:181], v141, s[100:101] offset:1024
	v_cmp_lt_i32_e32 vcc, v227, v226
	v_bfe_u32 v200, v132, 4, 2
	v_and_or_b32 v160, v132, 15, s8
	v_lshlrev_b32_e32 v132, 4, v200
	v_ashrrev_i32_e32 v161, 31, v160
	v_or_b32_e32 v156, 16, v160
	v_lshl_add_u64 v[188:189], s[16:17], 0, v[132:133]
	v_ashrrev_i32_e32 v157, 31, v156
	v_or_b32_e32 v152, 32, v160
	v_ashrrev_i32_e32 v153, 31, v152
	v_or_b32_e32 v150, 48, v160
	v_ashrrev_i32_e32 v151, 31, v150
	v_add_u32_e32 v146, 0x80, v160
	v_ashrrev_i32_e32 v147, 31, v146
	v_add_u32_e32 v144, 0x90, v160
	v_ashrrev_i32_e32 v145, 31, v144
	v_add_u32_e32 v142, 0xa0, v160
	v_add_u32_e32 v140, 0xb0, v160
	v_cndmask_b32_e32 v132, v253, v227, vcc
	v_lshlrev_b32_e32 v132, 2, v132
	v_xor_b32_e32 v145, 32, v253
	v_cmp_lt_i32_e32 vcc, v145, v226
	v_mov_b64_e32 v[196:197], s[30:31]
	s_waitcnt vmcnt(0)
	v_add_f32_e32 v174, v174, v175
	v_add_f32_e32 v176, v176, v177
	v_add_f32_e32 v178, v178, v179
	v_add_f32_e32 v180, v180, v181
	v_add_f32_e32 v174, v174, v176
	v_add_f32_e32 v178, v178, v180
	v_mov_b32_e32 v176, 0x358637bd
	s_nop 0
	v_add_f32_dpp v175, v174, v174 quad_perm:[1,0,3,2] row_mask:0xf bank_mask:0xf
	v_add_f32_dpp v179, v178, v178 quad_perm:[1,0,3,2] row_mask:0xf bank_mask:0xf
	v_and_b32_e32 v177, 60, v252
	v_lshl_add_u32 v177, v143, 7, v177
	v_add_f32_dpp v174, v175, v175 quad_perm:[2,3,0,1] row_mask:0xf bank_mask:0xf
	v_add_f32_dpp v178, v179, v179 quad_perm:[2,3,0,1] row_mask:0xf bank_mask:0xf
	v_add_u32_e32 v177, 0x21000, v177
	v_and_b32_e32 v180, 15, v252
	v_fmamk_f32 v174, v174, 0x3a800000, v176
	v_fmamk_f32 v178, v178, 0x3a800000, v176
	v_add_u32_e32 v180, s98, v180
	v_rsq_f32_e32 v174, v174
	v_rsq_f32_e32 v178, v178
	v_lshlrev_b32_e32 v180, 2, v180
	v_add_u32_e32 v180, 0x21000, v180
	ds_write_b32 v177, v174
	ds_write_b32 v177, v178 offset:64
	s_waitcnt lgkmcnt(0)
	s_barrier
	ds_read_b32 v168, v180
	ds_read_b32 v172, v180 offset:64
	ds_read_b32 v164, v180 offset:128
	ds_read_b32 v162, v180 offset:192
	ds_read_b32 v158, v180 offset:512
	ds_read_b32 v154, v180 offset:576
	ds_read_b32 v148, v180 offset:640
	ds_read_b32 v132, v180 offset:704
	s_waitcnt lgkmcnt(0)
	s_lshl_b32 s8, s63, 7
	v_lshl_or_b32 v141, v200, 3, s8
	v_pk_mul_f32 v[124:125], v[124:125], v[168:169] op_sel_hi:[1,0]
	v_or_b32_e32 v166, s57, v141
	v_mul_f32_e32 v141, 0xbfb8aa3b, v124
	v_exp_f32_e32 v141, v141
	v_mul_f32_e32 v143, 0xbfb8aa3b, v125
	v_exp_f32_e32 v143, v143
	v_pk_mul_f32 v[126:127], v[126:127], v[168:169] op_sel_hi:[1,0]
	v_add_f32_e32 v141, 1.0, v141
	v_rcp_f32_e32 v170, v141
	v_add_f32_e32 v141, 1.0, v143
	v_mul_f32_e32 v143, 0xbfb8aa3b, v126
	v_exp_f32_e32 v143, v143
	v_mul_f32_e32 v145, 0xbfb8aa3b, v127
	v_exp_f32_e32 v145, v145
	v_rcp_f32_e32 v171, v141
	v_add_f32_e32 v141, 1.0, v143
	v_rcp_f32_e32 v174, v141
	v_add_f32_e32 v141, 1.0, v145
	v_rcp_f32_e32 v175, v141
	v_pk_mul_f32 v[124:125], v[124:125], v[170:171]
	v_pk_mul_f32 v[116:117], v[116:117], v[168:169] op_sel_hi:[1,0]
	v_pk_mul_f32 v[120:121], v[120:121], v[168:169] op_sel_hi:[1,0]
	v_pk_mul_f32 v[116:117], v[116:117], v[124:125]
	v_pk_mul_f32 v[124:125], v[126:127], v[174:175]
	v_mul_f32_e32 v126, 0xbfb8aa3b, v120
	v_mul_f32_e32 v127, 0xbfb8aa3b, v121
	v_exp_f32_e32 v126, v126
	v_exp_f32_e32 v127, v127
	v_pk_mul_f32 v[118:119], v[118:119], v[168:169] op_sel_hi:[1,0]
	v_pk_mul_f32 v[122:123], v[122:123], v[168:169] op_sel_hi:[1,0]
	v_pk_mul_f32 v[118:119], v[118:119], v[124:125]
	v_add_f32_e32 v124, 1.0, v126
	v_add_f32_e32 v125, 1.0, v127
	v_mul_f32_e32 v126, 0xbfb8aa3b, v122
	v_mul_f32_e32 v127, 0xbfb8aa3b, v123
	v_exp_f32_e32 v126, v126
	v_exp_f32_e32 v127, v127
	v_rcp_f32_e32 v124, v124
	v_rcp_f32_e32 v125, v125
	v_add_f32_e32 v126, 1.0, v126
	v_add_f32_e32 v127, 1.0, v127
	v_rcp_f32_e32 v126, v126
	v_rcp_f32_e32 v127, v127
	v_pk_mul_f32 v[120:121], v[120:121], v[124:125]
	v_pk_mul_f32 v[112:113], v[112:113], v[168:169] op_sel_hi:[1,0]
	v_pk_mul_f32 v[114:115], v[114:115], v[168:169] op_sel_hi:[1,0]
	v_pk_mul_f32 v[112:113], v[112:113], v[120:121]
	v_pk_mul_f32 v[120:121], v[122:123], v[126:127]
	v_ashrrev_i32_e32 v167, 31, v166
	v_pk_mul_f32 v[114:115], v[114:115], v[120:121]
	v_cvt_pk_bf16_f32 v116, v116, v117
	v_cvt_pk_bf16_f32 v117, v118, v119
	v_cvt_pk_bf16_f32 v118, v112, v113
	v_mov_b64_e32 v[112:113], s[14:15]
	v_cvt_pk_bf16_f32 v119, v114, v115
	v_mad_i64_i32 v[120:121], s[8:9], v160, s62, v[112:113]
	v_lshlrev_b64 v[114:115], 1, v[166:167]
	v_pk_mul_f32 v[108:109], v[108:109], v[172:173] op_sel_hi:[1,0]
	v_lshl_add_u64 v[120:121], v[120:121], 0, v[114:115]
	v_mul_f32_e32 v122, 0xbfb8aa3b, v108
	v_mul_f32_e32 v123, 0xbfb8aa3b, v109
	v_pk_mul_f32 v[110:111], v[110:111], v[172:173] op_sel_hi:[1,0]
	v_exp_f32_e32 v122, v122
	v_exp_f32_e32 v123, v123
	global_store_dwordx4 v[120:121], v[116:119], off
	v_pk_mul_f32 v[100:101], v[100:101], v[172:173] op_sel_hi:[1,0]
	v_pk_mul_f32 v[104:105], v[104:105], v[172:173] op_sel_hi:[1,0]
	v_mul_f32_e32 v118, 0xbfb8aa3b, v110
	v_mul_f32_e32 v119, 0xbfb8aa3b, v111
	v_exp_f32_e32 v118, v118
	v_exp_f32_e32 v119, v119
	v_add_f32_e32 v116, 1.0, v122
	v_add_f32_e32 v117, 1.0, v123
	v_rcp_f32_e32 v116, v116
	v_rcp_f32_e32 v117, v117
	v_add_f32_e32 v118, 1.0, v118
	v_add_f32_e32 v119, 1.0, v119
	v_rcp_f32_e32 v118, v118
; #define PG8_GAS __attribute__((address_space(1)))
; __device__ __forceinline__ unsigned pk2_(float lo, float hi) { f32x2c_t v = {lo, hi}; bf16x2c_t b = __builtin_convertvector(v, bf16x2c_t); return __builtin_bit_cast(unsigned, b); }
; __device__ __forceinline__ float silu_f(float x) { return x * __builtin_amdgcn_rcpf(1.0f + __builtin_amdgcn_exp2f(-1.4426950408889634f * x)); }
;     __device__ __forceinline__ void operator()(const f32x4 (&acc)[2][2][4][2], const Unit& u, int wr, int wc, int fr, int fq) const {
;     ...
;             for (int m = 0; m < 4; ++m) {
;                 const int r = row0 + ai * HALF + m * 16; const float s = rs8[ai][m];
;                 float o[8];
; #pragma unroll
;                 for (int n = 0; n < 2; ++n)
; #pragma unroll
;                     for (int i = 0; i < 4; ++i) o[4 * n + i] = silu_f(acc[ai][0][m][n][i] * s) * (acc[ai][1][m][n][i] * s);
;                 u32x4 w; w.x = pk2_(o[0], o[1]); w.y = pk2_(o[2], o[3]); w.z = pk2_(o[4], o[5]); w.w = pk2_(o[6], o[7]);
;                 *(PG8_GAS u32x4*)(O + (size_t)r * 2816 + col0) = w;
	v_rcp_f32_e32 v119, v119
	v_pk_mul_f32 v[108:109], v[108:109], v[116:117]
	v_pk_mul_f32 v[102:103], v[102:103], v[172:173] op_sel_hi:[1,0]
	v_pk_mul_f32 v[100:101], v[100:101], v[108:109]
	v_pk_mul_f32 v[108:109], v[110:111], v[118:119]
	v_mul_f32_e32 v110, 0xbfb8aa3b, v104
	v_mul_f32_e32 v111, 0xbfb8aa3b, v105
	v_exp_f32_e32 v110, v110
	v_exp_f32_e32 v111, v111
	v_pk_mul_f32 v[106:107], v[106:107], v[172:173] op_sel_hi:[1,0]
	v_pk_mul_f32 v[102:103], v[102:103], v[108:109]
	v_add_f32_e32 v108, 1.0, v110
	v_add_f32_e32 v109, 1.0, v111
	v_mul_f32_e32 v110, 0xbfb8aa3b, v106
	v_mul_f32_e32 v111, 0xbfb8aa3b, v107
	v_exp_f32_e32 v110, v110
	v_exp_f32_e32 v111, v111
	v_rcp_f32_e32 v108, v108
	v_rcp_f32_e32 v109, v109
	v_add_f32_e32 v110, 1.0, v110
	v_add_f32_e32 v111, 1.0, v111
	v_rcp_f32_e32 v110, v110
	v_rcp_f32_e32 v111, v111
	v_pk_mul_f32 v[104:105], v[104:105], v[108:109]
	v_pk_mul_f32 v[96:97], v[96:97], v[172:173] op_sel_hi:[1,0]
	v_pk_mul_f32 v[98:99], v[98:99], v[172:173] op_sel_hi:[1,0]
	v_pk_mul_f32 v[104:105], v[96:97], v[104:105]
	v_pk_mul_f32 v[96:97], v[106:107], v[110:111]
	v_pk_mul_f32 v[92:93], v[92:93], v[164:165] op_sel_hi:[1,0]
	v_pk_mul_f32 v[106:107], v[98:99], v[96:97]
	v_cvt_pk_bf16_f32 v96, v100, v101
	v_mad_i64_i32 v[100:101], s[8:9], v156, s62, v[112:113]
	v_cvt_pk_bf16_f32 v97, v102, v103
	v_cvt_pk_bf16_f32 v98, v104, v105
	v_cvt_pk_bf16_f32 v99, v106, v107
	v_lshl_add_u64 v[100:101], v[100:101], 0, v[114:115]
	v_mul_f32_e32 v102, 0xbfb8aa3b, v92
	v_mul_f32_e32 v103, 0xbfb8aa3b, v93
	v_pk_mul_f32 v[94:95], v[94:95], v[164:165] op_sel_hi:[1,0]
	v_exp_f32_e32 v102, v102
	v_exp_f32_e32 v103, v103
	global_store_dwordx4 v[100:101], v[96:99], off
	v_pk_mul_f32 v[84:85], v[84:85], v[164:165] op_sel_hi:[1,0]
	v_pk_mul_f32 v[88:89], v[88:89], v[164:165] op_sel_hi:[1,0]
	v_mul_f32_e32 v98, 0xbfb8aa3b, v94
	v_mul_f32_e32 v99, 0xbfb8aa3b, v95
	v_exp_f32_e32 v98, v98
	v_exp_f32_e32 v99, v99
	v_add_f32_e32 v96, 1.0, v102
	v_add_f32_e32 v97, 1.0, v103
	v_rcp_f32_e32 v96, v96
	v_rcp_f32_e32 v97, v97
	v_add_f32_e32 v98, 1.0, v98
	v_add_f32_e32 v99, 1.0, v99
	v_rcp_f32_e32 v98, v98
	v_rcp_f32_e32 v99, v99
	v_pk_mul_f32 v[92:93], v[92:93], v[96:97]
	v_pk_mul_f32 v[86:87], v[86:87], v[164:165] op_sel_hi:[1,0]
	v_pk_mul_f32 v[84:85], v[84:85], v[92:93]
	v_pk_mul_f32 v[92:93], v[94:95], v[98:99]
	v_mul_f32_e32 v94, 0xbfb8aa3b, v88
	v_mul_f32_e32 v95, 0xbfb8aa3b, v89
	v_exp_f32_e32 v94, v94
	v_exp_f32_e32 v95, v95
	v_pk_mul_f32 v[90:91], v[90:91], v[164:165] op_sel_hi:[1,0]
	v_pk_mul_f32 v[86:87], v[86:87], v[92:93]
	v_add_f32_e32 v92, 1.0, v94
	v_add_f32_e32 v93, 1.0, v95
	v_mul_f32_e32 v94, 0xbfb8aa3b, v90
	v_mul_f32_e32 v95, 0xbfb8aa3b, v91
	v_exp_f32_e32 v94, v94
	v_exp_f32_e32 v95, v95
	v_rcp_f32_e32 v92, v92
	v_rcp_f32_e32 v93, v93
	v_add_f32_e32 v94, 1.0, v94
	v_add_f32_e32 v95, 1.0, v95
	v_rcp_f32_e32 v94, v94
	v_rcp_f32_e32 v95, v95
	v_pk_mul_f32 v[88:89], v[88:89], v[92:93]
	v_pk_mul_f32 v[80:81], v[80:81], v[164:165] op_sel_hi:[1,0]
	v_pk_mul_f32 v[82:83], v[82:83], v[164:165] op_sel_hi:[1,0]
	v_pk_mul_f32 v[88:89], v[80:81], v[88:89]
	v_pk_mul_f32 v[80:81], v[90:91], v[94:95]
	v_pk_mul_f32 v[76:77], v[76:77], v[162:163] op_sel_hi:[1,0]
	v_pk_mul_f32 v[90:91], v[82:83], v[80:81]
	v_cvt_pk_bf16_f32 v80, v84, v85
	v_mad_i64_i32 v[84:85], s[8:9], v152, s62, v[112:113]
	v_cvt_pk_bf16_f32 v81, v86, v87
	v_cvt_pk_bf16_f32 v82, v88, v89
	v_cvt_pk_bf16_f32 v83, v90, v91
	v_lshl_add_u64 v[84:85], v[84:85], 0, v[114:115]
	v_mul_f32_e32 v86, 0xbfb8aa3b, v76
	v_mul_f32_e32 v87, 0xbfb8aa3b, v77
	v_pk_mul_f32 v[78:79], v[78:79], v[162:163] op_sel_hi:[1,0]
	v_exp_f32_e32 v86, v86
	v_exp_f32_e32 v87, v87
	global_store_dwordx4 v[84:85], v[80:83], off
	v_pk_mul_f32 v[68:69], v[68:69], v[162:163] op_sel_hi:[1,0]
	v_pk_mul_f32 v[72:73], v[72:73], v[162:163] op_sel_hi:[1,0]
	v_mul_f32_e32 v82, 0xbfb8aa3b, v78
	v_mul_f32_e32 v83, 0xbfb8aa3b, v79
	v_exp_f32_e32 v82, v82
	v_exp_f32_e32 v83, v83
	v_add_f32_e32 v80, 1.0, v86
	v_add_f32_e32 v81, 1.0, v87
	v_rcp_f32_e32 v80, v80
	v_rcp_f32_e32 v81, v81
	v_add_f32_e32 v82, 1.0, v82
	v_add_f32_e32 v83, 1.0, v83
	v_rcp_f32_e32 v82, v82
	v_rcp_f32_e32 v83, v83
	v_pk_mul_f32 v[76:77], v[76:77], v[80:81]
	v_pk_mul_f32 v[70:71], v[70:71], v[162:163] op_sel_hi:[1,0]
	v_pk_mul_f32 v[68:69], v[68:69], v[76:77]
	v_pk_mul_f32 v[76:77], v[78:79], v[82:83]
	v_mul_f32_e32 v78, 0xbfb8aa3b, v72
	v_mul_f32_e32 v79, 0xbfb8aa3b, v73
	v_exp_f32_e32 v78, v78
	v_exp_f32_e32 v79, v79
	v_pk_mul_f32 v[74:75], v[74:75], v[162:163] op_sel_hi:[1,0]
	v_pk_mul_f32 v[70:71], v[70:71], v[76:77]
	v_add_f32_e32 v76, 1.0, v78
	v_add_f32_e32 v77, 1.0, v79
	v_mul_f32_e32 v78, 0xbfb8aa3b, v74
	v_mul_f32_e32 v79, 0xbfb8aa3b, v75
	v_exp_f32_e32 v78, v78
	v_exp_f32_e32 v79, v79
	v_rcp_f32_e32 v76, v76
	v_rcp_f32_e32 v77, v77
	v_add_f32_e32 v78, 1.0, v78
	v_add_f32_e32 v79, 1.0, v79
	v_rcp_f32_e32 v78, v78
	v_rcp_f32_e32 v79, v79
	v_pk_mul_f32 v[72:73], v[72:73], v[76:77]
	v_pk_mul_f32 v[64:65], v[64:65], v[162:163] op_sel_hi:[1,0]
	v_pk_mul_f32 v[66:67], v[66:67], v[162:163] op_sel_hi:[1,0]
	v_pk_mul_f32 v[72:73], v[64:65], v[72:73]
	v_pk_mul_f32 v[64:65], v[74:75], v[78:79]
	v_pk_mul_f32 v[60:61], v[60:61], v[158:159] op_sel_hi:[1,0]
	v_pk_mul_f32 v[74:75], v[66:67], v[64:65]
	v_cvt_pk_bf16_f32 v64, v68, v69
	v_mad_i64_i32 v[68:69], s[8:9], v150, s62, v[112:113]
	v_cvt_pk_bf16_f32 v65, v70, v71
	v_cvt_pk_bf16_f32 v66, v72, v73
	v_cvt_pk_bf16_f32 v67, v74, v75
	v_lshl_add_u64 v[68:69], v[68:69], 0, v[114:115]
	v_mul_f32_e32 v70, 0xbfb8aa3b, v60
	v_mul_f32_e32 v71, 0xbfb8aa3b, v61
	v_pk_mul_f32 v[62:63], v[62:63], v[158:159] op_sel_hi:[1,0]
; #define PG8_GAS __attribute__((address_space(1)))
; __device__ __forceinline__ unsigned pk2_(float lo, float hi) { f32x2c_t v = {lo, hi}; bf16x2c_t b = __builtin_convertvector(v, bf16x2c_t); return __builtin_bit_cast(unsigned, b); }
; __device__ __forceinline__ float silu_f(float x) { return x * __builtin_amdgcn_rcpf(1.0f + __builtin_amdgcn_exp2f(-1.4426950408889634f * x)); }
;     __device__ __forceinline__ void operator()(const f32x4 (&acc)[2][2][4][2], const Unit& u, int wr, int wc, int fr, int fq) const {
;     ...
;             for (int m = 0; m < 4; ++m) {
;                 const int r = row0 + ai * HALF + m * 16; const float s = rs8[ai][m];
;                 float o[8];
; #pragma unroll
;                 for (int n = 0; n < 2; ++n)
; #pragma unroll
;                     for (int i = 0; i < 4; ++i) o[4 * n + i] = silu_f(acc[ai][0][m][n][i] * s) * (acc[ai][1][m][n][i] * s);
;                 u32x4 w; w.x = pk2_(o[0], o[1]); w.y = pk2_(o[2], o[3]); w.z = pk2_(o[4], o[5]); w.w = pk2_(o[6], o[7]);
;                 *(PG8_GAS u32x4*)(O + (size_t)r * 2816 + col0) = w;
	v_exp_f32_e32 v70, v70
	v_exp_f32_e32 v71, v71
	global_store_dwordx4 v[68:69], v[64:67], off
	v_pk_mul_f32 v[52:53], v[52:53], v[158:159] op_sel_hi:[1,0]
	v_pk_mul_f32 v[56:57], v[56:57], v[158:159] op_sel_hi:[1,0]
	v_mul_f32_e32 v66, 0xbfb8aa3b, v62
	v_mul_f32_e32 v67, 0xbfb8aa3b, v63
	v_exp_f32_e32 v66, v66
	v_exp_f32_e32 v67, v67
	v_add_f32_e32 v64, 1.0, v70
	v_add_f32_e32 v65, 1.0, v71
	v_rcp_f32_e32 v64, v64
	v_rcp_f32_e32 v65, v65
	v_add_f32_e32 v66, 1.0, v66
	v_add_f32_e32 v67, 1.0, v67
	v_rcp_f32_e32 v66, v66
	v_rcp_f32_e32 v67, v67
	v_pk_mul_f32 v[60:61], v[60:61], v[64:65]
	v_pk_mul_f32 v[54:55], v[54:55], v[158:159] op_sel_hi:[1,0]
	v_pk_mul_f32 v[52:53], v[52:53], v[60:61]
	v_pk_mul_f32 v[60:61], v[62:63], v[66:67]
	v_mul_f32_e32 v62, 0xbfb8aa3b, v56
	v_mul_f32_e32 v63, 0xbfb8aa3b, v57
	v_exp_f32_e32 v62, v62
	v_exp_f32_e32 v63, v63
	v_pk_mul_f32 v[58:59], v[58:59], v[158:159] op_sel_hi:[1,0]
	v_pk_mul_f32 v[54:55], v[54:55], v[60:61]
	v_add_f32_e32 v60, 1.0, v62
	v_add_f32_e32 v61, 1.0, v63
	v_mul_f32_e32 v62, 0xbfb8aa3b, v58
	v_mul_f32_e32 v63, 0xbfb8aa3b, v59
	v_exp_f32_e32 v62, v62
	v_exp_f32_e32 v63, v63
	v_rcp_f32_e32 v60, v60
	v_rcp_f32_e32 v61, v61
	v_add_f32_e32 v62, 1.0, v62
	v_add_f32_e32 v63, 1.0, v63
	v_rcp_f32_e32 v62, v62
	v_rcp_f32_e32 v63, v63
	v_pk_mul_f32 v[56:57], v[56:57], v[60:61]
	v_pk_mul_f32 v[48:49], v[48:49], v[158:159] op_sel_hi:[1,0]
	v_pk_mul_f32 v[50:51], v[50:51], v[158:159] op_sel_hi:[1,0]
	v_pk_mul_f32 v[56:57], v[48:49], v[56:57]
	v_pk_mul_f32 v[48:49], v[58:59], v[62:63]
	v_pk_mul_f32 v[44:45], v[44:45], v[154:155] op_sel_hi:[1,0]
	v_pk_mul_f32 v[58:59], v[50:51], v[48:49]
	v_cvt_pk_bf16_f32 v48, v52, v53
	v_mad_i64_i32 v[52:53], s[8:9], v146, s62, v[112:113]
	v_cvt_pk_bf16_f32 v49, v54, v55
	v_cvt_pk_bf16_f32 v50, v56, v57
	v_cvt_pk_bf16_f32 v51, v58, v59
	v_lshl_add_u64 v[52:53], v[52:53], 0, v[114:115]
	v_mul_f32_e32 v54, 0xbfb8aa3b, v44
	v_mul_f32_e32 v55, 0xbfb8aa3b, v45
	v_pk_mul_f32 v[46:47], v[46:47], v[154:155] op_sel_hi:[1,0]
	v_exp_f32_e32 v54, v54
	v_exp_f32_e32 v55, v55
	global_store_dwordx4 v[52:53], v[48:51], off
	v_pk_mul_f32 v[36:37], v[36:37], v[154:155] op_sel_hi:[1,0]
	v_pk_mul_f32 v[40:41], v[40:41], v[154:155] op_sel_hi:[1,0]
	v_mul_f32_e32 v50, 0xbfb8aa3b, v46
	v_mul_f32_e32 v51, 0xbfb8aa3b, v47
	v_exp_f32_e32 v50, v50
	v_exp_f32_e32 v51, v51
	v_add_f32_e32 v48, 1.0, v54
	v_add_f32_e32 v49, 1.0, v55
	v_rcp_f32_e32 v48, v48
	v_rcp_f32_e32 v49, v49
	v_add_f32_e32 v50, 1.0, v50
	v_add_f32_e32 v51, 1.0, v51
	v_rcp_f32_e32 v50, v50
	v_rcp_f32_e32 v51, v51
	v_pk_mul_f32 v[44:45], v[44:45], v[48:49]
	v_pk_mul_f32 v[38:39], v[38:39], v[154:155] op_sel_hi:[1,0]
	v_pk_mul_f32 v[36:37], v[36:37], v[44:45]
	v_pk_mul_f32 v[44:45], v[46:47], v[50:51]
	v_mul_f32_e32 v46, 0xbfb8aa3b, v40
	v_mul_f32_e32 v47, 0xbfb8aa3b, v41
	v_exp_f32_e32 v46, v46
	v_exp_f32_e32 v47, v47
	v_pk_mul_f32 v[42:43], v[42:43], v[154:155] op_sel_hi:[1,0]
	v_pk_mul_f32 v[38:39], v[38:39], v[44:45]
	v_add_f32_e32 v44, 1.0, v46
	v_add_f32_e32 v45, 1.0, v47
	v_mul_f32_e32 v46, 0xbfb8aa3b, v42
	v_mul_f32_e32 v47, 0xbfb8aa3b, v43
	v_exp_f32_e32 v46, v46
	v_exp_f32_e32 v47, v47
	v_rcp_f32_e32 v44, v44
	v_rcp_f32_e32 v45, v45
	v_add_f32_e32 v46, 1.0, v46
	v_add_f32_e32 v47, 1.0, v47
	v_rcp_f32_e32 v46, v46
	v_rcp_f32_e32 v47, v47
	v_pk_mul_f32 v[40:41], v[40:41], v[44:45]
	v_pk_mul_f32 v[32:33], v[32:33], v[154:155] op_sel_hi:[1,0]
	v_pk_mul_f32 v[34:35], v[34:35], v[154:155] op_sel_hi:[1,0]
	v_pk_mul_f32 v[40:41], v[32:33], v[40:41]
	v_pk_mul_f32 v[32:33], v[42:43], v[46:47]
	v_pk_mul_f32 v[28:29], v[28:29], v[148:149] op_sel_hi:[1,0]
	v_pk_mul_f32 v[42:43], v[34:35], v[32:33]
	v_cvt_pk_bf16_f32 v32, v36, v37
	v_mad_i64_i32 v[36:37], s[8:9], v144, s62, v[112:113]
	v_cvt_pk_bf16_f32 v33, v38, v39
	v_cvt_pk_bf16_f32 v34, v40, v41
	v_cvt_pk_bf16_f32 v35, v42, v43
	v_lshl_add_u64 v[36:37], v[36:37], 0, v[114:115]
	v_mul_f32_e32 v38, 0xbfb8aa3b, v28
	v_mul_f32_e32 v39, 0xbfb8aa3b, v29
	v_pk_mul_f32 v[30:31], v[30:31], v[148:149] op_sel_hi:[1,0]
; #define PG8_GAS __attribute__((address_space(1)))
; __device__ __forceinline__ unsigned pk2_(float lo, float hi) { f32x2c_t v = {lo, hi}; bf16x2c_t b = __builtin_convertvector(v, bf16x2c_t); return __builtin_bit_cast(unsigned, b); }
; __device__ __forceinline__ float silu_f(float x) { return x * __builtin_amdgcn_rcpf(1.0f + __builtin_amdgcn_exp2f(-1.4426950408889634f * x)); }
;     __device__ __forceinline__ void operator()(const f32x4 (&acc)[2][2][4][2], const Unit& u, int wr, int wc, int fr, int fq) const {
;     ...
;             for (int m = 0; m < 4; ++m) {
;                 const int r = row0 + ai * HALF + m * 16; const float s = rs8[ai][m];
;                 float o[8];
; #pragma unroll
;                 for (int n = 0; n < 2; ++n)
; #pragma unroll
;                     for (int i = 0; i < 4; ++i) o[4 * n + i] = silu_f(acc[ai][0][m][n][i] * s) * (acc[ai][1][m][n][i] * s);
;                 u32x4 w; w.x = pk2_(o[0], o[1]); w.y = pk2_(o[2], o[3]); w.z = pk2_(o[4], o[5]); w.w = pk2_(o[6], o[7]);
;                 *(PG8_GAS u32x4*)(O + (size_t)r * 2816 + col0) = w;
	v_exp_f32_e32 v38, v38
	v_exp_f32_e32 v39, v39
	global_store_dwordx4 v[36:37], v[32:35], off
	v_pk_mul_f32 v[20:21], v[20:21], v[148:149] op_sel_hi:[1,0]
	v_pk_mul_f32 v[24:25], v[24:25], v[148:149] op_sel_hi:[1,0]
	v_mul_f32_e32 v34, 0xbfb8aa3b, v30
	v_mul_f32_e32 v35, 0xbfb8aa3b, v31
	v_exp_f32_e32 v34, v34
	v_exp_f32_e32 v35, v35
	v_add_f32_e32 v32, 1.0, v38
	v_add_f32_e32 v33, 1.0, v39
	v_rcp_f32_e32 v32, v32
	v_rcp_f32_e32 v33, v33
	v_add_f32_e32 v34, 1.0, v34
	v_add_f32_e32 v35, 1.0, v35
	v_rcp_f32_e32 v34, v34
	v_rcp_f32_e32 v35, v35
	v_pk_mul_f32 v[28:29], v[28:29], v[32:33]
	v_pk_mul_f32 v[22:23], v[22:23], v[148:149] op_sel_hi:[1,0]
	v_pk_mul_f32 v[20:21], v[20:21], v[28:29]
	v_pk_mul_f32 v[28:29], v[30:31], v[34:35]
	v_mul_f32_e32 v30, 0xbfb8aa3b, v24
	v_mul_f32_e32 v31, 0xbfb8aa3b, v25
	v_exp_f32_e32 v30, v30
	v_exp_f32_e32 v31, v31
	v_pk_mul_f32 v[26:27], v[26:27], v[148:149] op_sel_hi:[1,0]
	v_pk_mul_f32 v[22:23], v[22:23], v[28:29]
	v_add_f32_e32 v28, 1.0, v30
	v_add_f32_e32 v29, 1.0, v31
	v_mul_f32_e32 v30, 0xbfb8aa3b, v26
	v_mul_f32_e32 v31, 0xbfb8aa3b, v27
	v_exp_f32_e32 v30, v30
	v_exp_f32_e32 v31, v31
	v_rcp_f32_e32 v28, v28
	v_rcp_f32_e32 v29, v29
	v_add_f32_e32 v30, 1.0, v30
	v_add_f32_e32 v31, 1.0, v31
	v_rcp_f32_e32 v30, v30
	v_rcp_f32_e32 v31, v31
	v_pk_mul_f32 v[24:25], v[24:25], v[28:29]
	v_pk_mul_f32 v[16:17], v[16:17], v[148:149] op_sel_hi:[1,0]
	v_pk_mul_f32 v[18:19], v[18:19], v[148:149] op_sel_hi:[1,0]
	v_pk_mul_f32 v[24:25], v[16:17], v[24:25]
	v_pk_mul_f32 v[16:17], v[26:27], v[30:31]
	v_pk_mul_f32 v[12:13], v[12:13], v[132:133] op_sel_hi:[1,0]
	v_pk_mul_f32 v[26:27], v[18:19], v[16:17]
	v_cvt_pk_bf16_f32 v16, v20, v21
	v_mad_i64_i32 v[20:21], s[8:9], v142, s62, v[112:113]
	v_cvt_pk_bf16_f32 v17, v22, v23
	v_cvt_pk_bf16_f32 v18, v24, v25
	v_cvt_pk_bf16_f32 v19, v26, v27
	v_lshl_add_u64 v[20:21], v[20:21], 0, v[114:115]
	v_mul_f32_e32 v22, 0xbfb8aa3b, v12
	v_mul_f32_e32 v23, 0xbfb8aa3b, v13
	v_pk_mul_f32 v[14:15], v[14:15], v[132:133] op_sel_hi:[1,0]
	v_exp_f32_e32 v22, v22
	v_exp_f32_e32 v23, v23
	global_store_dwordx4 v[20:21], v[16:19], off
	v_pk_mul_f32 v[4:5], v[4:5], v[132:133] op_sel_hi:[1,0]
	v_pk_mul_f32 v[8:9], v[8:9], v[132:133] op_sel_hi:[1,0]
	v_mul_f32_e32 v18, 0xbfb8aa3b, v14
	v_mul_f32_e32 v19, 0xbfb8aa3b, v15
	v_exp_f32_e32 v18, v18
	v_exp_f32_e32 v19, v19
	v_add_f32_e32 v16, 1.0, v22
	v_add_f32_e32 v17, 1.0, v23
	v_rcp_f32_e32 v16, v16
	v_rcp_f32_e32 v17, v17
	v_add_f32_e32 v18, 1.0, v18
	v_add_f32_e32 v19, 1.0, v19
	v_rcp_f32_e32 v18, v18
	v_rcp_f32_e32 v19, v19
	v_pk_mul_f32 v[12:13], v[12:13], v[16:17]
	v_pk_mul_f32 v[6:7], v[6:7], v[132:133] op_sel_hi:[1,0]
	v_pk_mul_f32 v[4:5], v[4:5], v[12:13]
	v_pk_mul_f32 v[12:13], v[14:15], v[18:19]
	v_mul_f32_e32 v14, 0xbfb8aa3b, v8
	v_mul_f32_e32 v15, 0xbfb8aa3b, v9
	v_exp_f32_e32 v14, v14
	v_exp_f32_e32 v15, v15
	v_pk_mul_f32 v[10:11], v[10:11], v[132:133] op_sel_hi:[1,0]
	v_pk_mul_f32 v[6:7], v[6:7], v[12:13]
	v_add_f32_e32 v12, 1.0, v14
	v_add_f32_e32 v13, 1.0, v15
	v_mul_f32_e32 v14, 0xbfb8aa3b, v10
	v_mul_f32_e32 v15, 0xbfb8aa3b, v11
	v_exp_f32_e32 v14, v14
	v_exp_f32_e32 v15, v15
	v_rcp_f32_e32 v12, v12
	v_rcp_f32_e32 v13, v13
	v_add_f32_e32 v14, 1.0, v14
	v_add_f32_e32 v15, 1.0, v15
	v_rcp_f32_e32 v14, v14
	v_rcp_f32_e32 v15, v15
	v_pk_mul_f32 v[8:9], v[8:9], v[12:13]
	v_pk_mul_f32 v[0:1], v[0:1], v[132:133] op_sel_hi:[1,0]
	v_pk_mul_f32 v[2:3], v[2:3], v[132:133] op_sel_hi:[1,0]
	v_pk_mul_f32 v[8:9], v[0:1], v[8:9]
	v_pk_mul_f32 v[0:1], v[10:11], v[14:15]
	s_andn2_b64 vcc, exec, s[6:7]
	v_pk_mul_f32 v[10:11], v[2:3], v[0:1]
	v_cvt_pk_bf16_f32 v0, v4, v5
	v_mad_i64_i32 v[4:5], s[8:9], v140, s62, v[112:113]
	v_cvt_pk_bf16_f32 v1, v6, v7
	v_cvt_pk_bf16_f32 v2, v8, v9
	v_cvt_pk_bf16_f32 v3, v10, v11
	v_lshl_add_u64 v[4:5], v[4:5], 0, v[114:115]
	s_mov_b64 s[6:7], -1
	global_store_dwordx4 v[4:5], v[0:3], off
	s_cbranch_vccnz .LBB0_1654
	s_andn2_b64 vcc, exec, s[12:13]
	s_cbranch_vccnz .LBB0_1653
	s_barrier
	s_branch .LBB0_1653
